# K-loop back-edge rotation (simple form): pointer/counter updates and exit compare moved ahead of the loop-back barrier in all 7 GEMM loops; on top of H7
# baseline (speedup 1.0000x reference)
.LBB0_904:
	s_add_i32 s69, s8, 2
	s_add_u32 s0, s52, 0xfff80080
	s_addc_u32 s1, s53, -1
	s_add_i32 s70, 0, 0x10000
	s_cmp_eq_u32 s66, s8
	s_cselect_b32 s59, s41, s1
	s_cselect_b32 s58, s45, s0
	s_cselect_b32 s9, s43, s68
	s_cselect_b32 s8, s65, s67
	s_add_i32 s0, 0, 0x14000
	v_add_u32_e32 v156, s70, v141
	v_add_u32_e32 v172, s0, v141
	ds_read_b128 v[144:147], v156
	ds_read_b128 v[148:151], v156 offset:1024
	ds_read_b128 v[152:155], v156 offset:2048
	ds_read_b128 v[156:159], v156 offset:3072
	ds_read_b128 v[160:163], v172
	ds_read_b128 v[164:167], v172 offset:1024
	ds_read_b128 v[168:171], v172 offset:2048
	ds_read_b128 v[172:175], v172 offset:3072
	v_lshl_add_u64 v[214:215], s[52:53], 0, v[138:139]
	s_add_i32 m0, s27, 0xc000
	ds_read_b128 v[176:179], v143
	ds_read_b128 v[180:183], v143 offset:1024
	ds_read_b128 v[184:187], v143 offset:2048
	ds_read_b128 v[188:191], v143 offset:3072
	ds_read_b128 v[192:195], v143 offset:4096
	ds_read_b128 v[202:205], v143 offset:5120
	ds_read_b128 v[206:209], v143 offset:6144
	ds_read_b128 v[210:213], v143 offset:7168
	global_load_lds_dwordx4 v[214:215], off
	v_lshl_add_u64 v[214:215], s[52:53], 0, v[136:137]
	s_add_i32 m0, s27, 0xe000
	s_nop 0
	global_load_lds_dwordx4 v[214:215], off
	s_waitcnt vmcnt(8)
	s_waitcnt lgkmcnt(0)
	s_barrier
	s_setprio 1
	s_waitcnt lgkmcnt(0)
	v_mfma_f32_16x16x32_bf16 v[126:129], v[144:147], v[176:179], v[126:129]
	v_mfma_f32_16x16x32_bf16 v[118:121], v[152:155], v[176:179], v[118:121]
	v_mfma_f32_16x16x32_bf16 v[110:113], v[144:147], v[184:187], v[110:113]
	v_mfma_f32_16x16x32_bf16 v[102:105], v[152:155], v[184:187], v[102:105]
	v_mfma_f32_16x16x32_bf16 v[94:97], v[144:147], v[192:195], v[94:97]
	v_mfma_f32_16x16x32_bf16 v[86:89], v[152:155], v[192:195], v[86:89]
	v_mfma_f32_16x16x32_bf16 v[78:81], v[144:147], v[206:209], v[78:81]
	v_mfma_f32_16x16x32_bf16 v[70:73], v[152:155], v[206:209], v[70:73]
	v_mfma_f32_16x16x32_bf16 v[126:129], v[148:151], v[180:183], v[126:129]
	v_mfma_f32_16x16x32_bf16 v[118:121], v[156:159], v[180:183], v[118:121]
	v_mfma_f32_16x16x32_bf16 v[110:113], v[148:151], v[188:191], v[110:113]
	v_mfma_f32_16x16x32_bf16 v[102:105], v[156:159], v[188:191], v[102:105]
	v_mfma_f32_16x16x32_bf16 v[94:97], v[148:151], v[202:205], v[94:97]
	v_mfma_f32_16x16x32_bf16 v[86:89], v[156:159], v[202:205], v[86:89]
	v_mfma_f32_16x16x32_bf16 v[78:81], v[148:151], v[210:213], v[78:81]
	v_mfma_f32_16x16x32_bf16 v[70:73], v[156:159], v[210:213], v[70:73]
	s_setprio 0
	s_setprio 1
	v_mfma_f32_16x16x32_bf16 v[122:125], v[160:163], v[176:179], v[122:125]
	v_mfma_f32_16x16x32_bf16 v[114:117], v[168:171], v[176:179], v[114:117]
	v_mfma_f32_16x16x32_bf16 v[106:109], v[160:163], v[184:187], v[106:109]
	v_mfma_f32_16x16x32_bf16 v[98:101], v[168:171], v[184:187], v[98:101]
	v_mfma_f32_16x16x32_bf16 v[90:93], v[160:163], v[192:195], v[90:93]
	v_mfma_f32_16x16x32_bf16 v[82:85], v[168:171], v[192:195], v[82:85]
	v_mfma_f32_16x16x32_bf16 v[74:77], v[160:163], v[206:209], v[74:77]
	v_mfma_f32_16x16x32_bf16 v[66:69], v[168:171], v[206:209], v[66:69]
	v_mfma_f32_16x16x32_bf16 v[122:125], v[164:167], v[180:183], v[122:125]
	v_mfma_f32_16x16x32_bf16 v[114:117], v[172:175], v[180:183], v[114:117]
	v_mfma_f32_16x16x32_bf16 v[106:109], v[164:167], v[188:191], v[106:109]
	v_mfma_f32_16x16x32_bf16 v[98:101], v[172:175], v[188:191], v[98:101]
	v_mfma_f32_16x16x32_bf16 v[90:93], v[164:167], v[202:205], v[90:93]
	v_mfma_f32_16x16x32_bf16 v[82:85], v[172:175], v[202:205], v[82:85]
	v_mfma_f32_16x16x32_bf16 v[74:77], v[164:167], v[210:213], v[74:77]
	v_mfma_f32_16x16x32_bf16 v[66:69], v[172:175], v[210:213], v[66:69]
	s_setprio 0
	s_barrier
	s_add_i32 s1, s70, s26
	v_lshl_add_u64 v[214:215], s[8:9], 0, v[196:197]
	s_mov_b32 m0, s1
	ds_read_b128 v[176:179], v143 offset:16384
	ds_read_b128 v[180:183], v143 offset:17408
	ds_read_b128 v[184:187], v143 offset:18432
	ds_read_b128 v[188:191], v143 offset:19456
	ds_read_b128 v[192:195], v143 offset:20480
	ds_read_b128 v[202:205], v143 offset:21504
	ds_read_b128 v[206:209], v143 offset:22528
	ds_read_b128 v[210:213], v143 offset:23552
	global_load_lds_dwordx4 v[214:215], off
	s_add_i32 m0, s1, 0x2000
	s_add_u32 s70, s8, 0x80000
	v_lshl_add_u64 v[216:217], s[8:9], 0, v[130:131]
	s_addc_u32 s71, s9, 0
	s_add_i32 s0, s0, s26
	global_load_lds_dwordx4 v[216:217], off
	v_lshl_add_u64 v[218:219], s[70:71], 0, v[196:197]
	s_mov_b32 m0, s0
	v_lshl_add_u64 v[220:221], s[58:59], 0, v[132:133]
	global_load_lds_dwordx4 v[218:219], off
	v_lshl_add_u64 v[218:219], s[70:71], 0, v[130:131]
	s_add_i32 m0, s0, 0x2000
	s_nop 0
	global_load_lds_dwordx4 v[218:219], off
	v_lshl_add_u64 v[218:219], s[58:59], 0, v[134:135]
	s_mov_b32 m0, s27
	s_nop 0
	global_load_lds_dwordx4 v[218:219], off
	s_mov_b32 m0, s28
	s_nop 0
	global_load_lds_dwordx4 v[220:221], off
	s_waitcnt vmcnt(8)
	s_waitcnt lgkmcnt(0)
	s_barrier
	s_setprio 1
	s_waitcnt lgkmcnt(0)
	v_mfma_f32_16x16x32_bf16 v[62:65], v[144:147], v[176:179], v[62:65]
	v_mfma_f32_16x16x32_bf16 v[54:57], v[152:155], v[176:179], v[54:57]
	v_mfma_f32_16x16x32_bf16 v[46:49], v[144:147], v[184:187], v[46:49]
	v_mfma_f32_16x16x32_bf16 v[38:41], v[152:155], v[184:187], v[38:41]
	v_mfma_f32_16x16x32_bf16 v[30:33], v[144:147], v[192:195], v[30:33]
	v_mfma_f32_16x16x32_bf16 v[22:25], v[152:155], v[192:195], v[22:25]
	v_mfma_f32_16x16x32_bf16 v[14:17], v[144:147], v[206:209], v[14:17]
	v_mfma_f32_16x16x32_bf16 v[6:9], v[152:155], v[206:209], v[6:9]
	v_mfma_f32_16x16x32_bf16 v[62:65], v[148:151], v[180:183], v[62:65]
	v_mfma_f32_16x16x32_bf16 v[54:57], v[156:159], v[180:183], v[54:57]
	v_mfma_f32_16x16x32_bf16 v[46:49], v[148:151], v[188:191], v[46:49]
	v_mfma_f32_16x16x32_bf16 v[38:41], v[156:159], v[188:191], v[38:41]
	v_mfma_f32_16x16x32_bf16 v[30:33], v[148:151], v[202:205], v[30:33]
	v_mfma_f32_16x16x32_bf16 v[22:25], v[156:159], v[202:205], v[22:25]
	v_mfma_f32_16x16x32_bf16 v[14:17], v[148:151], v[210:213], v[14:17]
	v_mfma_f32_16x16x32_bf16 v[6:9], v[156:159], v[210:213], v[6:9]
	s_setprio 0
	s_setprio 1
	v_mfma_f32_16x16x32_bf16 v[58:61], v[160:163], v[176:179], v[58:61]
	v_mfma_f32_16x16x32_bf16 v[50:53], v[168:171], v[176:179], v[50:53]
	v_mfma_f32_16x16x32_bf16 v[42:45], v[160:163], v[184:187], v[42:45]
	v_mfma_f32_16x16x32_bf16 v[34:37], v[168:171], v[184:187], v[34:37]
	v_mfma_f32_16x16x32_bf16 v[26:29], v[160:163], v[192:195], v[26:29]
	v_mfma_f32_16x16x32_bf16 v[18:21], v[168:171], v[192:195], v[18:21]
	v_mfma_f32_16x16x32_bf16 v[10:13], v[160:163], v[206:209], v[10:13]
	v_mfma_f32_16x16x32_bf16 v[2:5], v[168:171], v[206:209], v[2:5]
	v_mfma_f32_16x16x32_bf16 v[58:61], v[164:167], v[180:183], v[58:61]
	v_mfma_f32_16x16x32_bf16 v[50:53], v[172:175], v[180:183], v[50:53]
	v_mfma_f32_16x16x32_bf16 v[42:45], v[164:167], v[188:191], v[42:45]
	v_mfma_f32_16x16x32_bf16 v[34:37], v[172:175], v[188:191], v[34:37]
	v_mfma_f32_16x16x32_bf16 v[26:29], v[164:167], v[202:205], v[26:29]
	v_mfma_f32_16x16x32_bf16 v[18:21], v[172:175], v[202:205], v[18:21]
	v_mfma_f32_16x16x32_bf16 v[10:13], v[164:167], v[210:213], v[10:13]
	v_mfma_f32_16x16x32_bf16 v[2:5], v[172:175], v[210:213], v[2:5]
	s_setprio 0
	s_barrier
	s_add_i32 s0, 0, 0x18000
	s_add_i32 s1, 0, 0x1c000
	v_add_u32_e32 v156, s0, v141
	v_add_u32_e32 v172, s1, v141
	ds_read_b128 v[144:147], v156
	ds_read_b128 v[148:151], v156 offset:1024
	ds_read_b128 v[152:155], v156 offset:2048
	ds_read_b128 v[156:159], v156 offset:3072
	ds_read_b128 v[160:163], v172
	ds_read_b128 v[164:167], v172 offset:1024
	ds_read_b128 v[168:171], v172 offset:2048
	ds_read_b128 v[172:175], v172 offset:3072
	s_add_u32 s58, s58, 0x80000
	s_addc_u32 s59, s59, 0
	s_mov_b32 m0, s29
	v_lshl_add_u64 v[222:223], s[58:59], 0, v[134:135]
	ds_read_b128 v[176:179], v143 offset:32768
	ds_read_b128 v[180:183], v143 offset:33792
	ds_read_b128 v[184:187], v143 offset:34816
	ds_read_b128 v[188:191], v143 offset:35840
	ds_read_b128 v[192:195], v143 offset:36864
	ds_read_b128 v[202:205], v143 offset:37888
	ds_read_b128 v[206:209], v143 offset:38912
	ds_read_b128 v[210:213], v143 offset:39936
	global_load_lds_dwordx4 v[222:223], off
	v_lshl_add_u64 v[222:223], s[58:59], 0, v[132:133]
	s_mov_b32 m0, s30
	s_nop 0
	global_load_lds_dwordx4 v[222:223], off
	s_waitcnt vmcnt(8)
	s_waitcnt lgkmcnt(0)
	s_barrier
	s_setprio 1
	s_waitcnt lgkmcnt(0)
	v_mfma_f32_16x16x32_bf16 v[126:129], v[144:147], v[176:179], v[126:129]
	v_mfma_f32_16x16x32_bf16 v[118:121], v[152:155], v[176:179], v[118:121]
	v_mfma_f32_16x16x32_bf16 v[110:113], v[144:147], v[184:187], v[110:113]
	v_mfma_f32_16x16x32_bf16 v[102:105], v[152:155], v[184:187], v[102:105]
	v_mfma_f32_16x16x32_bf16 v[94:97], v[144:147], v[192:195], v[94:97]
	v_mfma_f32_16x16x32_bf16 v[86:89], v[152:155], v[192:195], v[86:89]
	v_mfma_f32_16x16x32_bf16 v[78:81], v[144:147], v[206:209], v[78:81]
	v_mfma_f32_16x16x32_bf16 v[70:73], v[152:155], v[206:209], v[70:73]
	v_mfma_f32_16x16x32_bf16 v[126:129], v[148:151], v[180:183], v[126:129]
	v_mfma_f32_16x16x32_bf16 v[118:121], v[156:159], v[180:183], v[118:121]
	v_mfma_f32_16x16x32_bf16 v[110:113], v[148:151], v[188:191], v[110:113]
	v_mfma_f32_16x16x32_bf16 v[102:105], v[156:159], v[188:191], v[102:105]
	v_mfma_f32_16x16x32_bf16 v[94:97], v[148:151], v[202:205], v[94:97]
	v_mfma_f32_16x16x32_bf16 v[86:89], v[156:159], v[202:205], v[86:89]
	v_mfma_f32_16x16x32_bf16 v[78:81], v[148:151], v[210:213], v[78:81]
	v_mfma_f32_16x16x32_bf16 v[70:73], v[156:159], v[210:213], v[70:73]
	s_setprio 0
	s_setprio 1
	v_mfma_f32_16x16x32_bf16 v[122:125], v[160:163], v[176:179], v[122:125]
	v_mfma_f32_16x16x32_bf16 v[114:117], v[168:171], v[176:179], v[114:117]
	v_mfma_f32_16x16x32_bf16 v[106:109], v[160:163], v[184:187], v[106:109]
	v_mfma_f32_16x16x32_bf16 v[98:101], v[168:171], v[184:187], v[98:101]
	v_mfma_f32_16x16x32_bf16 v[90:93], v[160:163], v[192:195], v[90:93]
	v_mfma_f32_16x16x32_bf16 v[82:85], v[168:171], v[192:195], v[82:85]
	v_mfma_f32_16x16x32_bf16 v[74:77], v[160:163], v[206:209], v[74:77]
	v_mfma_f32_16x16x32_bf16 v[66:69], v[168:171], v[206:209], v[66:69]
	v_mfma_f32_16x16x32_bf16 v[122:125], v[164:167], v[180:183], v[122:125]
	v_mfma_f32_16x16x32_bf16 v[114:117], v[172:175], v[180:183], v[114:117]
	v_mfma_f32_16x16x32_bf16 v[106:109], v[164:167], v[188:191], v[106:109]
	v_mfma_f32_16x16x32_bf16 v[98:101], v[172:175], v[188:191], v[98:101]
	v_mfma_f32_16x16x32_bf16 v[90:93], v[164:167], v[202:205], v[90:93]
	v_mfma_f32_16x16x32_bf16 v[82:85], v[172:175], v[202:205], v[82:85]
	v_mfma_f32_16x16x32_bf16 v[74:77], v[164:167], v[210:213], v[74:77]
	v_mfma_f32_16x16x32_bf16 v[66:69], v[172:175], v[210:213], v[66:69]
	s_setprio 0
	s_barrier
	s_add_i32 s0, s0, s26
	v_lshl_add_u64 v[214:215], v[214:215], 0, s[16:17]
	s_mov_b32 m0, s0
	ds_read_b128 v[176:179], v143 offset:49152
	ds_read_b128 v[180:183], v143 offset:50176
	ds_read_b128 v[184:187], v143 offset:51200
	ds_read_b128 v[188:191], v143 offset:52224
	ds_read_b128 v[192:195], v143 offset:53248
	ds_read_b128 v[202:205], v143 offset:54272
	ds_read_b128 v[206:209], v143 offset:55296
	ds_read_b128 v[210:213], v143 offset:56320
	global_load_lds_dwordx4 v[214:215], off
	s_add_i32 m0, s0, 0x2000
	s_add_u32 s8, s8, 0x80080
	v_lshl_add_u64 v[214:215], v[216:217], 0, s[16:17]
	s_addc_u32 s9, s9, 0
	s_add_i32 s0, s1, s26
	global_load_lds_dwordx4 v[214:215], off
	v_lshl_add_u64 v[214:215], s[8:9], 0, v[196:197]
	s_mov_b32 m0, s0
	s_nop 0
	global_load_lds_dwordx4 v[214:215], off
	v_lshl_add_u64 v[214:215], s[8:9], 0, v[130:131]
	s_add_i32 m0, s0, 0x2000
	s_nop 0
	global_load_lds_dwordx4 v[214:215], off
	v_lshl_add_u64 v[214:215], v[218:219], 0, s[16:17]
	s_mov_b32 m0, s31
	s_nop 0
	global_load_lds_dwordx4 v[214:215], off
	v_lshl_add_u64 v[214:215], v[220:221], 0, s[16:17]
	s_mov_b32 m0, s34
	s_nop 0
	global_load_lds_dwordx4 v[214:215], off
	s_waitcnt vmcnt(8)
	s_waitcnt lgkmcnt(0)
	s_barrier
	s_setprio 1
	s_waitcnt lgkmcnt(0)
	v_mfma_f32_16x16x32_bf16 v[62:65], v[144:147], v[176:179], v[62:65]
	v_mfma_f32_16x16x32_bf16 v[54:57], v[152:155], v[176:179], v[54:57]
	v_mfma_f32_16x16x32_bf16 v[46:49], v[144:147], v[184:187], v[46:49]
	v_mfma_f32_16x16x32_bf16 v[38:41], v[152:155], v[184:187], v[38:41]
	v_mfma_f32_16x16x32_bf16 v[30:33], v[144:147], v[192:195], v[30:33]
	v_mfma_f32_16x16x32_bf16 v[22:25], v[152:155], v[192:195], v[22:25]
	v_mfma_f32_16x16x32_bf16 v[14:17], v[144:147], v[206:209], v[14:17]
	v_mfma_f32_16x16x32_bf16 v[6:9], v[152:155], v[206:209], v[6:9]
	v_mfma_f32_16x16x32_bf16 v[62:65], v[148:151], v[180:183], v[62:65]
	v_mfma_f32_16x16x32_bf16 v[54:57], v[156:159], v[180:183], v[54:57]
	v_mfma_f32_16x16x32_bf16 v[46:49], v[148:151], v[188:191], v[46:49]
	v_mfma_f32_16x16x32_bf16 v[38:41], v[156:159], v[188:191], v[38:41]
	v_mfma_f32_16x16x32_bf16 v[30:33], v[148:151], v[202:205], v[30:33]
	v_mfma_f32_16x16x32_bf16 v[22:25], v[156:159], v[202:205], v[22:25]
	v_mfma_f32_16x16x32_bf16 v[14:17], v[148:151], v[210:213], v[14:17]
	v_mfma_f32_16x16x32_bf16 v[6:9], v[156:159], v[210:213], v[6:9]
	s_setprio 0
	s_setprio 1
	v_mfma_f32_16x16x32_bf16 v[58:61], v[160:163], v[176:179], v[58:61]
	v_mfma_f32_16x16x32_bf16 v[50:53], v[168:171], v[176:179], v[50:53]
	v_mfma_f32_16x16x32_bf16 v[42:45], v[160:163], v[184:187], v[42:45]
	v_mfma_f32_16x16x32_bf16 v[34:37], v[168:171], v[184:187], v[34:37]
	v_mfma_f32_16x16x32_bf16 v[26:29], v[160:163], v[192:195], v[26:29]
	v_mfma_f32_16x16x32_bf16 v[18:21], v[168:171], v[192:195], v[18:21]
	v_mfma_f32_16x16x32_bf16 v[10:13], v[160:163], v[206:209], v[10:13]
	v_mfma_f32_16x16x32_bf16 v[2:5], v[168:171], v[206:209], v[2:5]
	v_mfma_f32_16x16x32_bf16 v[58:61], v[164:167], v[180:183], v[58:61]
	v_mfma_f32_16x16x32_bf16 v[50:53], v[172:175], v[180:183], v[50:53]
	v_mfma_f32_16x16x32_bf16 v[42:45], v[164:167], v[188:191], v[42:45]
	v_mfma_f32_16x16x32_bf16 v[34:37], v[172:175], v[188:191], v[34:37]
	v_mfma_f32_16x16x32_bf16 v[26:29], v[164:167], v[202:205], v[26:29]
	v_mfma_f32_16x16x32_bf16 v[18:21], v[172:175], v[202:205], v[18:21]
	v_mfma_f32_16x16x32_bf16 v[10:13], v[164:167], v[210:213], v[10:13]
	v_mfma_f32_16x16x32_bf16 v[2:5], v[172:175], v[210:213], v[2:5]
	s_add_u32 s67, s67, 0x100
	s_addc_u32 s68, s68, 0
	s_add_u32 s52, s52, 0x100
	s_addc_u32 s53, s53, 0
	s_cmp_ge_i32 s69, s62
	s_mov_b32 s8, s69
	s_setprio 0
	s_barrier
	s_cbranch_scc0 .LBB0_904
	s_and_b64 vcc, exec, s[38:39]
	s_cbranch_vccz .LBB0_907
	s_barrier

.LBB0_987:
	s_add_i32 s72, s50, 2
	s_add_u32 s8, s48, 0x100
	s_addc_u32 s9, s49, 0
	s_add_i32 s0, 0, 0x10000
	s_cmp_eq_u32 s41, s50
	s_cselect_b32 s53, s45, s9
	s_cselect_b32 s52, s44, s8
	s_cselect_b32 s51, s47, s71
	s_cselect_b32 s50, s46, s70
	s_add_i32 s1, 0, 0x14000
	v_add_u32_e32 v142, s0, v188
	v_add_u32_e32 v172, s1, v188
	ds_read_b128 v[130:133], v142
	ds_read_b128 v[134:137], v142 offset:1024
	ds_read_b128 v[138:141], v142 offset:2048
	ds_read_b128 v[142:145], v142 offset:3072
	ds_read_b128 v[146:149], v172
	ds_read_b128 v[164:167], v172 offset:1024
	ds_read_b128 v[168:171], v172 offset:2048
	ds_read_b128 v[172:175], v172 offset:3072
	v_lshl_add_u64 v[194:195], s[48:49], 0, v[162:163]
	s_add_i32 m0, s27, 0xc000
	ds_read_b128 v[176:179], v189
	ds_read_b128 v[180:183], v189 offset:1024
	ds_read_b128 v[184:187], v189 offset:2048
	ds_read_b128 v[190:193], v189 offset:3072
	ds_read_b128 v[202:205], v189 offset:4096
	ds_read_b128 v[206:209], v189 offset:5120
	ds_read_b128 v[210:213], v189 offset:6144
	ds_read_b128 v[214:217], v189 offset:7168
	global_load_lds_dwordx4 v[194:195], off
	v_lshl_add_u64 v[194:195], s[48:49], 0, v[160:161]
	s_add_i32 m0, s27, 0xe000
	s_nop 0
	global_load_lds_dwordx4 v[194:195], off
	s_waitcnt vmcnt(8)
	s_waitcnt lgkmcnt(0)
	s_barrier
	s_setprio 1
	s_waitcnt lgkmcnt(0)
	v_mfma_f32_16x16x32_bf16 v[126:129], v[130:133], v[176:179], v[126:129]
	v_mfma_f32_16x16x32_bf16 v[122:125], v[138:141], v[176:179], v[122:125]
	v_mfma_f32_16x16x32_bf16 v[110:113], v[130:133], v[184:187], v[110:113]
	v_mfma_f32_16x16x32_bf16 v[106:109], v[138:141], v[184:187], v[106:109]
	v_mfma_f32_16x16x32_bf16 v[98:101], v[130:133], v[202:205], v[98:101]
	v_mfma_f32_16x16x32_bf16 v[90:93], v[138:141], v[202:205], v[90:93]
	v_mfma_f32_16x16x32_bf16 v[82:85], v[130:133], v[210:213], v[82:85]
	v_mfma_f32_16x16x32_bf16 v[74:77], v[138:141], v[210:213], v[74:77]
	v_mfma_f32_16x16x32_bf16 v[126:129], v[134:137], v[180:183], v[126:129]
	v_mfma_f32_16x16x32_bf16 v[122:125], v[142:145], v[180:183], v[122:125]
	v_mfma_f32_16x16x32_bf16 v[110:113], v[134:137], v[190:193], v[110:113]
	v_mfma_f32_16x16x32_bf16 v[106:109], v[142:145], v[190:193], v[106:109]
	v_mfma_f32_16x16x32_bf16 v[98:101], v[134:137], v[206:209], v[98:101]
	v_mfma_f32_16x16x32_bf16 v[90:93], v[142:145], v[206:209], v[90:93]
	v_mfma_f32_16x16x32_bf16 v[82:85], v[134:137], v[214:217], v[82:85]
	v_mfma_f32_16x16x32_bf16 v[74:77], v[142:145], v[214:217], v[74:77]
	s_setprio 0
	s_setprio 1
	v_mfma_f32_16x16x32_bf16 v[118:121], v[146:149], v[176:179], v[118:121]
	v_mfma_f32_16x16x32_bf16 v[114:117], v[168:171], v[176:179], v[114:117]
	v_mfma_f32_16x16x32_bf16 v[102:105], v[146:149], v[184:187], v[102:105]
	v_mfma_f32_16x16x32_bf16 v[94:97], v[168:171], v[184:187], v[94:97]
	v_mfma_f32_16x16x32_bf16 v[86:89], v[146:149], v[202:205], v[86:89]
	v_mfma_f32_16x16x32_bf16 v[78:81], v[168:171], v[202:205], v[78:81]
	v_mfma_f32_16x16x32_bf16 v[70:73], v[146:149], v[210:213], v[70:73]
	v_mfma_f32_16x16x32_bf16 v[66:69], v[168:171], v[210:213], v[66:69]
	v_mfma_f32_16x16x32_bf16 v[118:121], v[164:167], v[180:183], v[118:121]
	v_mfma_f32_16x16x32_bf16 v[114:117], v[172:175], v[180:183], v[114:117]
	v_mfma_f32_16x16x32_bf16 v[102:105], v[164:167], v[190:193], v[102:105]
	v_mfma_f32_16x16x32_bf16 v[94:97], v[172:175], v[190:193], v[94:97]
	v_mfma_f32_16x16x32_bf16 v[86:89], v[164:167], v[206:209], v[86:89]
	v_mfma_f32_16x16x32_bf16 v[78:81], v[172:175], v[206:209], v[78:81]
	v_mfma_f32_16x16x32_bf16 v[70:73], v[164:167], v[214:217], v[70:73]
	v_mfma_f32_16x16x32_bf16 v[66:69], v[172:175], v[214:217], v[66:69]
	s_setprio 0
	s_barrier
	s_add_i32 s0, s0, s26
	v_lshl_add_u64 v[194:195], s[50:51], 0, v[196:197]
	s_mov_b32 m0, s0
	ds_read_b128 v[176:179], v189 offset:16384
	ds_read_b128 v[180:183], v189 offset:17408
	ds_read_b128 v[184:187], v189 offset:18432
	ds_read_b128 v[190:193], v189 offset:19456
	ds_read_b128 v[202:205], v189 offset:20480
	ds_read_b128 v[206:209], v189 offset:21504
	ds_read_b128 v[210:213], v189 offset:22528
	ds_read_b128 v[214:217], v189 offset:23552
	global_load_lds_dwordx4 v[194:195], off
	s_add_i32 m0, s0, 0x2000
	s_add_u32 s48, s50, 0x158000
	v_lshl_add_u64 v[218:219], s[50:51], 0, v[154:155]
	s_addc_u32 s49, s51, 0
	s_add_i32 s0, s1, s26
	global_load_lds_dwordx4 v[218:219], off
	v_lshl_add_u64 v[220:221], s[48:49], 0, v[196:197]
	s_mov_b32 m0, s0
	v_lshl_add_u64 v[222:223], s[52:53], 0, v[152:153]
	global_load_lds_dwordx4 v[220:221], off
	v_lshl_add_u64 v[220:221], s[48:49], 0, v[154:155]
	s_add_i32 m0, s0, 0x2000
	s_nop 0
	global_load_lds_dwordx4 v[220:221], off
	v_lshl_add_u64 v[220:221], s[52:53], 0, v[150:151]
	s_mov_b32 m0, s27
	s_nop 0
	global_load_lds_dwordx4 v[220:221], off
	s_mov_b32 m0, s28
	s_nop 0
	global_load_lds_dwordx4 v[222:223], off
	s_waitcnt vmcnt(8)
	s_waitcnt lgkmcnt(0)
	s_barrier
	s_setprio 1
	s_waitcnt lgkmcnt(0)
	v_mfma_f32_16x16x32_bf16 v[62:65], v[130:133], v[176:179], v[62:65]
	v_mfma_f32_16x16x32_bf16 v[58:61], v[138:141], v[176:179], v[58:61]
	v_mfma_f32_16x16x32_bf16 v[50:53], v[130:133], v[184:187], v[50:53]
	v_mfma_f32_16x16x32_bf16 v[42:45], v[138:141], v[184:187], v[42:45]
	v_mfma_f32_16x16x32_bf16 v[34:37], v[130:133], v[202:205], v[34:37]
	v_mfma_f32_16x16x32_bf16 v[26:29], v[138:141], v[202:205], v[26:29]
	v_mfma_f32_16x16x32_bf16 v[18:21], v[130:133], v[210:213], v[18:21]
	v_mfma_f32_16x16x32_bf16 v[10:13], v[138:141], v[210:213], v[10:13]
	v_mfma_f32_16x16x32_bf16 v[62:65], v[134:137], v[180:183], v[62:65]
	v_mfma_f32_16x16x32_bf16 v[58:61], v[142:145], v[180:183], v[58:61]
	v_mfma_f32_16x16x32_bf16 v[50:53], v[134:137], v[190:193], v[50:53]
	v_mfma_f32_16x16x32_bf16 v[42:45], v[142:145], v[190:193], v[42:45]
	v_mfma_f32_16x16x32_bf16 v[34:37], v[134:137], v[206:209], v[34:37]
	v_mfma_f32_16x16x32_bf16 v[26:29], v[142:145], v[206:209], v[26:29]
	v_mfma_f32_16x16x32_bf16 v[18:21], v[134:137], v[214:217], v[18:21]
	v_mfma_f32_16x16x32_bf16 v[10:13], v[142:145], v[214:217], v[10:13]
	s_setprio 0
	s_setprio 1
	v_mfma_f32_16x16x32_bf16 v[54:57], v[146:149], v[176:179], v[54:57]
	v_mfma_f32_16x16x32_bf16 v[46:49], v[168:171], v[176:179], v[46:49]
	v_mfma_f32_16x16x32_bf16 v[38:41], v[146:149], v[184:187], v[38:41]
	v_mfma_f32_16x16x32_bf16 v[30:33], v[168:171], v[184:187], v[30:33]
	v_mfma_f32_16x16x32_bf16 v[22:25], v[146:149], v[202:205], v[22:25]
	v_mfma_f32_16x16x32_bf16 v[14:17], v[168:171], v[202:205], v[14:17]
	v_mfma_f32_16x16x32_bf16 v[6:9], v[146:149], v[210:213], v[6:9]
	v_mfma_f32_16x16x32_bf16 v[2:5], v[168:171], v[210:213], v[2:5]
	v_mfma_f32_16x16x32_bf16 v[54:57], v[164:167], v[180:183], v[54:57]
	v_mfma_f32_16x16x32_bf16 v[46:49], v[172:175], v[180:183], v[46:49]
	v_mfma_f32_16x16x32_bf16 v[38:41], v[164:167], v[190:193], v[38:41]
	v_mfma_f32_16x16x32_bf16 v[30:33], v[172:175], v[190:193], v[30:33]
	v_mfma_f32_16x16x32_bf16 v[22:25], v[164:167], v[206:209], v[22:25]
	v_mfma_f32_16x16x32_bf16 v[14:17], v[172:175], v[206:209], v[14:17]
	v_mfma_f32_16x16x32_bf16 v[6:9], v[164:167], v[214:217], v[6:9]
	v_mfma_f32_16x16x32_bf16 v[2:5], v[172:175], v[214:217], v[2:5]
	s_setprio 0
	s_barrier
	s_add_i32 s0, 0, 0x18000
	s_add_i32 s1, 0, 0x1c000
	v_add_u32_e32 v142, s0, v188
	v_add_u32_e32 v172, s1, v188
	ds_read_b128 v[130:133], v142
	ds_read_b128 v[134:137], v142 offset:1024
	ds_read_b128 v[138:141], v142 offset:2048
	ds_read_b128 v[142:145], v142 offset:3072
	ds_read_b128 v[146:149], v172
	ds_read_b128 v[164:167], v172 offset:1024
	ds_read_b128 v[168:171], v172 offset:2048
	ds_read_b128 v[172:175], v172 offset:3072
	s_add_u32 s48, s52, 0x158000
	s_addc_u32 s49, s53, 0
	s_mov_b32 m0, s29
	v_lshl_add_u64 v[224:225], s[48:49], 0, v[150:151]
	ds_read_b128 v[176:179], v189 offset:32768
	ds_read_b128 v[180:183], v189 offset:33792
	ds_read_b128 v[184:187], v189 offset:34816
	ds_read_b128 v[190:193], v189 offset:35840
	ds_read_b128 v[202:205], v189 offset:36864
	ds_read_b128 v[206:209], v189 offset:37888
	ds_read_b128 v[210:213], v189 offset:38912
	ds_read_b128 v[214:217], v189 offset:39936
	global_load_lds_dwordx4 v[224:225], off
	v_lshl_add_u64 v[224:225], s[48:49], 0, v[152:153]
	s_mov_b32 m0, s30
	s_nop 0
	global_load_lds_dwordx4 v[224:225], off
	s_waitcnt vmcnt(8)
	s_waitcnt lgkmcnt(0)
	s_barrier
	s_setprio 1
	s_waitcnt lgkmcnt(0)
	v_mfma_f32_16x16x32_bf16 v[126:129], v[130:133], v[176:179], v[126:129]
	v_mfma_f32_16x16x32_bf16 v[122:125], v[138:141], v[176:179], v[122:125]
	v_mfma_f32_16x16x32_bf16 v[110:113], v[130:133], v[184:187], v[110:113]
	v_mfma_f32_16x16x32_bf16 v[106:109], v[138:141], v[184:187], v[106:109]
	v_mfma_f32_16x16x32_bf16 v[98:101], v[130:133], v[202:205], v[98:101]
	v_mfma_f32_16x16x32_bf16 v[90:93], v[138:141], v[202:205], v[90:93]
	v_mfma_f32_16x16x32_bf16 v[82:85], v[130:133], v[210:213], v[82:85]
	v_mfma_f32_16x16x32_bf16 v[74:77], v[138:141], v[210:213], v[74:77]
	v_mfma_f32_16x16x32_bf16 v[126:129], v[134:137], v[180:183], v[126:129]
	v_mfma_f32_16x16x32_bf16 v[122:125], v[142:145], v[180:183], v[122:125]
	v_mfma_f32_16x16x32_bf16 v[110:113], v[134:137], v[190:193], v[110:113]
	v_mfma_f32_16x16x32_bf16 v[106:109], v[142:145], v[190:193], v[106:109]
	v_mfma_f32_16x16x32_bf16 v[98:101], v[134:137], v[206:209], v[98:101]
	v_mfma_f32_16x16x32_bf16 v[90:93], v[142:145], v[206:209], v[90:93]
	v_mfma_f32_16x16x32_bf16 v[82:85], v[134:137], v[214:217], v[82:85]
	v_mfma_f32_16x16x32_bf16 v[74:77], v[142:145], v[214:217], v[74:77]
	s_setprio 0
	s_setprio 1
	v_mfma_f32_16x16x32_bf16 v[118:121], v[146:149], v[176:179], v[118:121]
	v_mfma_f32_16x16x32_bf16 v[114:117], v[168:171], v[176:179], v[114:117]
	v_mfma_f32_16x16x32_bf16 v[102:105], v[146:149], v[184:187], v[102:105]
	v_mfma_f32_16x16x32_bf16 v[94:97], v[168:171], v[184:187], v[94:97]
	v_mfma_f32_16x16x32_bf16 v[86:89], v[146:149], v[202:205], v[86:89]
	v_mfma_f32_16x16x32_bf16 v[78:81], v[168:171], v[202:205], v[78:81]
	v_mfma_f32_16x16x32_bf16 v[70:73], v[146:149], v[210:213], v[70:73]
	v_mfma_f32_16x16x32_bf16 v[66:69], v[168:171], v[210:213], v[66:69]
	v_mfma_f32_16x16x32_bf16 v[118:121], v[164:167], v[180:183], v[118:121]
	v_mfma_f32_16x16x32_bf16 v[114:117], v[172:175], v[180:183], v[114:117]
	v_mfma_f32_16x16x32_bf16 v[102:105], v[164:167], v[190:193], v[102:105]
	v_mfma_f32_16x16x32_bf16 v[94:97], v[172:175], v[190:193], v[94:97]
	v_mfma_f32_16x16x32_bf16 v[86:89], v[164:167], v[206:209], v[86:89]
	v_mfma_f32_16x16x32_bf16 v[78:81], v[172:175], v[206:209], v[78:81]
	v_mfma_f32_16x16x32_bf16 v[70:73], v[164:167], v[214:217], v[70:73]
	v_mfma_f32_16x16x32_bf16 v[66:69], v[172:175], v[214:217], v[66:69]
	s_setprio 0
	s_barrier
	s_add_i32 s0, s0, s26
	v_lshl_add_u64 v[194:195], v[194:195], 0, s[16:17]
	s_mov_b32 m0, s0
	ds_read_b128 v[176:179], v189 offset:49152
	ds_read_b128 v[180:183], v189 offset:50176
	ds_read_b128 v[184:187], v189 offset:51200
	ds_read_b128 v[190:193], v189 offset:52224
	ds_read_b128 v[202:205], v189 offset:53248
	ds_read_b128 v[206:209], v189 offset:54272
	ds_read_b128 v[210:213], v189 offset:55296
	ds_read_b128 v[214:217], v189 offset:56320
	global_load_lds_dwordx4 v[194:195], off
	s_add_i32 m0, s0, 0x2000
	s_add_u32 s48, s50, 0x158080
	v_lshl_add_u64 v[194:195], v[218:219], 0, s[16:17]
	s_addc_u32 s49, s51, 0
	s_add_i32 s0, s1, s26
	global_load_lds_dwordx4 v[194:195], off
	v_lshl_add_u64 v[194:195], s[48:49], 0, v[196:197]
	s_mov_b32 m0, s0
	s_nop 0
	global_load_lds_dwordx4 v[194:195], off
	v_lshl_add_u64 v[194:195], s[48:49], 0, v[154:155]
	s_add_i32 m0, s0, 0x2000
	s_nop 0
	global_load_lds_dwordx4 v[194:195], off
	v_lshl_add_u64 v[194:195], v[220:221], 0, s[16:17]
	s_mov_b32 m0, s35
	s_nop 0
	global_load_lds_dwordx4 v[194:195], off
	v_lshl_add_u64 v[194:195], v[222:223], 0, s[16:17]
	s_mov_b32 m0, s58
	s_nop 0
	global_load_lds_dwordx4 v[194:195], off
	s_waitcnt vmcnt(8)
	s_waitcnt lgkmcnt(0)
	s_barrier
	s_setprio 1
	s_waitcnt lgkmcnt(0)
	v_mfma_f32_16x16x32_bf16 v[62:65], v[130:133], v[176:179], v[62:65]
	v_mfma_f32_16x16x32_bf16 v[58:61], v[138:141], v[176:179], v[58:61]
	v_mfma_f32_16x16x32_bf16 v[50:53], v[130:133], v[184:187], v[50:53]
	v_mfma_f32_16x16x32_bf16 v[42:45], v[138:141], v[184:187], v[42:45]
	v_mfma_f32_16x16x32_bf16 v[34:37], v[130:133], v[202:205], v[34:37]
	v_mfma_f32_16x16x32_bf16 v[26:29], v[138:141], v[202:205], v[26:29]
	v_mfma_f32_16x16x32_bf16 v[18:21], v[130:133], v[210:213], v[18:21]
	v_mfma_f32_16x16x32_bf16 v[10:13], v[138:141], v[210:213], v[10:13]
	v_mfma_f32_16x16x32_bf16 v[62:65], v[134:137], v[180:183], v[62:65]
	v_mfma_f32_16x16x32_bf16 v[58:61], v[142:145], v[180:183], v[58:61]
	v_mfma_f32_16x16x32_bf16 v[50:53], v[134:137], v[190:193], v[50:53]
	v_mfma_f32_16x16x32_bf16 v[42:45], v[142:145], v[190:193], v[42:45]
	v_mfma_f32_16x16x32_bf16 v[34:37], v[134:137], v[206:209], v[34:37]
	v_mfma_f32_16x16x32_bf16 v[26:29], v[142:145], v[206:209], v[26:29]
	v_mfma_f32_16x16x32_bf16 v[18:21], v[134:137], v[214:217], v[18:21]
	v_mfma_f32_16x16x32_bf16 v[10:13], v[142:145], v[214:217], v[10:13]
	s_setprio 0
	s_setprio 1
	v_mfma_f32_16x16x32_bf16 v[54:57], v[146:149], v[176:179], v[54:57]
	v_mfma_f32_16x16x32_bf16 v[46:49], v[168:171], v[176:179], v[46:49]
	v_mfma_f32_16x16x32_bf16 v[38:41], v[146:149], v[184:187], v[38:41]
	v_mfma_f32_16x16x32_bf16 v[30:33], v[168:171], v[184:187], v[30:33]
	v_mfma_f32_16x16x32_bf16 v[22:25], v[146:149], v[202:205], v[22:25]
	v_mfma_f32_16x16x32_bf16 v[14:17], v[168:171], v[202:205], v[14:17]
	v_mfma_f32_16x16x32_bf16 v[6:9], v[146:149], v[210:213], v[6:9]
	v_mfma_f32_16x16x32_bf16 v[2:5], v[168:171], v[210:213], v[2:5]
	v_mfma_f32_16x16x32_bf16 v[54:57], v[164:167], v[180:183], v[54:57]
	v_mfma_f32_16x16x32_bf16 v[46:49], v[172:175], v[180:183], v[46:49]
	v_mfma_f32_16x16x32_bf16 v[38:41], v[164:167], v[190:193], v[38:41]
	v_mfma_f32_16x16x32_bf16 v[30:33], v[172:175], v[190:193], v[30:33]
	v_mfma_f32_16x16x32_bf16 v[22:25], v[164:167], v[206:209], v[22:25]
	v_mfma_f32_16x16x32_bf16 v[14:17], v[172:175], v[206:209], v[14:17]
	v_mfma_f32_16x16x32_bf16 v[6:9], v[164:167], v[214:217], v[6:9]
	v_mfma_f32_16x16x32_bf16 v[2:5], v[172:175], v[214:217], v[2:5]
	s_add_u32 s70, s70, 0x100
	s_addc_u32 s71, s71, 0
	s_cmp_ge_i32 s72, s69
	s_mov_b64 s[48:49], s[8:9]
	s_mov_b32 s50, s72
	s_setprio 0
	s_barrier
	s_cbranch_scc0 .LBB0_987
	s_and_b64 vcc, exec, s[38:39]
	s_cbranch_vccz .LBB0_990
	s_barrier

.LBB0_1135:
	s_add_i32 s71, s8, 2
	s_add_u32 s0, s58, 0xfff80080
	s_addc_u32 s1, s59, -1
	s_add_i32 s72, 0, 0x10000
	s_cmp_eq_u32 s68, s8
	s_cselect_b32 s63, s43, s1
	s_cselect_b32 s62, s47, s0
	v_add_u32_e32 v146, s72, v149
	s_cselect_b32 s9, s45, s70
	s_cselect_b32 s8, s67, s69
	s_add_i32 s0, 0, 0x14000
	ds_read_b128 v[142:145], v146
	ds_read_b128 v[152:155], v146 offset:1024
	ds_read_b128 v[156:159], v146 offset:2048
	ds_read_b128 v[160:163], v146 offset:3072
	v_add_u32_e32 v146, s0, v149
	ds_read_b128 v[164:167], v146
	ds_read_b128 v[168:171], v146 offset:1024
	ds_read_b128 v[172:175], v146 offset:2048
	ds_read_b128 v[176:179], v146 offset:3072
	v_lshl_add_u64 v[146:147], s[58:59], 0, v[140:141]
	s_add_i32 m0, s27, 0xc000
	ds_read_b128 v[180:183], v151
	ds_read_b128 v[184:187], v151 offset:1024
	ds_read_b128 v[188:191], v151 offset:2048
	ds_read_b128 v[192:195], v151 offset:3072
	ds_read_b128 v[202:205], v151 offset:4096
	ds_read_b128 v[206:209], v151 offset:5120
	ds_read_b128 v[210:213], v151 offset:6144
	ds_read_b128 v[214:217], v151 offset:7168
	global_load_lds_dwordx4 v[146:147], off
	v_lshl_add_u64 v[146:147], s[58:59], 0, v[138:139]
	s_add_i32 m0, s27, 0xe000
	s_nop 0
	global_load_lds_dwordx4 v[146:147], off
	s_waitcnt vmcnt(8)
	s_waitcnt lgkmcnt(0)
	s_barrier
	s_setprio 1
	s_waitcnt lgkmcnt(0)
	v_mfma_f32_16x16x32_bf16 v[126:129], v[142:145], v[180:183], v[126:129]
	v_mfma_f32_16x16x32_bf16 v[122:125], v[156:159], v[180:183], v[122:125]
	v_mfma_f32_16x16x32_bf16 v[118:121], v[142:145], v[188:191], v[118:121]
	v_mfma_f32_16x16x32_bf16 v[110:113], v[156:159], v[188:191], v[110:113]
	v_mfma_f32_16x16x32_bf16 v[102:105], v[142:145], v[202:205], v[102:105]
	v_mfma_f32_16x16x32_bf16 v[94:97], v[156:159], v[202:205], v[94:97]
	v_mfma_f32_16x16x32_bf16 v[86:89], v[142:145], v[210:213], v[86:89]
	v_mfma_f32_16x16x32_bf16 v[78:81], v[156:159], v[210:213], v[78:81]
	v_mfma_f32_16x16x32_bf16 v[126:129], v[152:155], v[184:187], v[126:129]
	v_mfma_f32_16x16x32_bf16 v[122:125], v[160:163], v[184:187], v[122:125]
	v_mfma_f32_16x16x32_bf16 v[118:121], v[152:155], v[192:195], v[118:121]
	v_mfma_f32_16x16x32_bf16 v[110:113], v[160:163], v[192:195], v[110:113]
	v_mfma_f32_16x16x32_bf16 v[102:105], v[152:155], v[206:209], v[102:105]
	v_mfma_f32_16x16x32_bf16 v[94:97], v[160:163], v[206:209], v[94:97]
	v_mfma_f32_16x16x32_bf16 v[86:89], v[152:155], v[214:217], v[86:89]
	v_mfma_f32_16x16x32_bf16 v[78:81], v[160:163], v[214:217], v[78:81]
	s_setprio 0
	s_setprio 1
	v_mfma_f32_16x16x32_bf16 v[114:117], v[164:167], v[180:183], v[114:117]
	v_mfma_f32_16x16x32_bf16 v[106:109], v[172:175], v[180:183], v[106:109]
	v_mfma_f32_16x16x32_bf16 v[98:101], v[164:167], v[188:191], v[98:101]
	v_mfma_f32_16x16x32_bf16 v[90:93], v[172:175], v[188:191], v[90:93]
	v_mfma_f32_16x16x32_bf16 v[82:85], v[164:167], v[202:205], v[82:85]
	v_mfma_f32_16x16x32_bf16 v[74:77], v[172:175], v[202:205], v[74:77]
	v_mfma_f32_16x16x32_bf16 v[70:73], v[164:167], v[210:213], v[70:73]
	v_mfma_f32_16x16x32_bf16 v[66:69], v[172:175], v[210:213], v[66:69]
	v_mfma_f32_16x16x32_bf16 v[114:117], v[168:171], v[184:187], v[114:117]
	v_mfma_f32_16x16x32_bf16 v[106:109], v[176:179], v[184:187], v[106:109]
	v_mfma_f32_16x16x32_bf16 v[98:101], v[168:171], v[192:195], v[98:101]
	v_mfma_f32_16x16x32_bf16 v[90:93], v[176:179], v[192:195], v[90:93]
	v_mfma_f32_16x16x32_bf16 v[82:85], v[168:171], v[206:209], v[82:85]
	v_mfma_f32_16x16x32_bf16 v[74:77], v[176:179], v[206:209], v[74:77]
	v_mfma_f32_16x16x32_bf16 v[70:73], v[168:171], v[214:217], v[70:73]
	v_mfma_f32_16x16x32_bf16 v[66:69], v[176:179], v[214:217], v[66:69]
	s_setprio 0
	s_barrier
	s_add_i32 s1, s72, s26
	v_lshl_add_u64 v[146:147], s[8:9], 0, v[196:197]
	s_mov_b32 m0, s1
	ds_read_b128 v[180:183], v151 offset:16384
	ds_read_b128 v[184:187], v151 offset:17408
	ds_read_b128 v[188:191], v151 offset:18432
	ds_read_b128 v[192:195], v151 offset:19456
	ds_read_b128 v[202:205], v151 offset:20480
	ds_read_b128 v[206:209], v151 offset:21504
	ds_read_b128 v[210:213], v151 offset:22528
	ds_read_b128 v[214:217], v151 offset:23552
	global_load_lds_dwordx4 v[146:147], off
	s_add_i32 m0, s1, 0x2000
	s_add_u32 s72, s8, 0x80000
	v_lshl_add_u64 v[218:219], s[8:9], 0, v[130:131]
	s_addc_u32 s73, s9, 0
	s_add_i32 s0, s0, s26
	global_load_lds_dwordx4 v[218:219], off
	v_lshl_add_u64 v[220:221], s[72:73], 0, v[196:197]
	s_mov_b32 m0, s0
	v_lshl_add_u64 v[222:223], s[62:63], 0, v[132:133]
	global_load_lds_dwordx4 v[220:221], off
	v_lshl_add_u64 v[220:221], s[72:73], 0, v[130:131]
	s_add_i32 m0, s0, 0x2000
	s_nop 0
	global_load_lds_dwordx4 v[220:221], off
	v_lshl_add_u64 v[220:221], s[62:63], 0, v[134:135]
	s_mov_b32 m0, s27
	s_nop 0
	global_load_lds_dwordx4 v[220:221], off
	s_mov_b32 m0, s28
	s_nop 0
	global_load_lds_dwordx4 v[222:223], off
	s_waitcnt vmcnt(8)
	s_waitcnt lgkmcnt(0)
	s_barrier
	s_setprio 1
	s_waitcnt lgkmcnt(0)
	v_mfma_f32_16x16x32_bf16 v[62:65], v[142:145], v[180:183], v[62:65]
	v_mfma_f32_16x16x32_bf16 v[58:61], v[156:159], v[180:183], v[58:61]
	v_mfma_f32_16x16x32_bf16 v[54:57], v[142:145], v[188:191], v[54:57]
	v_mfma_f32_16x16x32_bf16 v[46:49], v[156:159], v[188:191], v[46:49]
	v_mfma_f32_16x16x32_bf16 v[38:41], v[142:145], v[202:205], v[38:41]
	v_mfma_f32_16x16x32_bf16 v[30:33], v[156:159], v[202:205], v[30:33]
	v_mfma_f32_16x16x32_bf16 v[22:25], v[142:145], v[210:213], v[22:25]
	v_mfma_f32_16x16x32_bf16 v[14:17], v[156:159], v[210:213], v[14:17]
	v_mfma_f32_16x16x32_bf16 v[62:65], v[152:155], v[184:187], v[62:65]
	v_mfma_f32_16x16x32_bf16 v[58:61], v[160:163], v[184:187], v[58:61]
	v_mfma_f32_16x16x32_bf16 v[54:57], v[152:155], v[192:195], v[54:57]
	v_mfma_f32_16x16x32_bf16 v[46:49], v[160:163], v[192:195], v[46:49]
	v_mfma_f32_16x16x32_bf16 v[38:41], v[152:155], v[206:209], v[38:41]
	v_mfma_f32_16x16x32_bf16 v[30:33], v[160:163], v[206:209], v[30:33]
	v_mfma_f32_16x16x32_bf16 v[22:25], v[152:155], v[214:217], v[22:25]
	v_mfma_f32_16x16x32_bf16 v[14:17], v[160:163], v[214:217], v[14:17]
	s_setprio 0
	s_setprio 1
	v_mfma_f32_16x16x32_bf16 v[50:53], v[164:167], v[180:183], v[50:53]
	v_mfma_f32_16x16x32_bf16 v[42:45], v[172:175], v[180:183], v[42:45]
	v_mfma_f32_16x16x32_bf16 v[34:37], v[164:167], v[188:191], v[34:37]
	v_mfma_f32_16x16x32_bf16 v[26:29], v[172:175], v[188:191], v[26:29]
	v_mfma_f32_16x16x32_bf16 v[18:21], v[164:167], v[202:205], v[18:21]
	v_mfma_f32_16x16x32_bf16 v[10:13], v[172:175], v[202:205], v[10:13]
	v_mfma_f32_16x16x32_bf16 v[6:9], v[164:167], v[210:213], v[6:9]
	v_mfma_f32_16x16x32_bf16 v[2:5], v[172:175], v[210:213], v[2:5]
	v_mfma_f32_16x16x32_bf16 v[50:53], v[168:171], v[184:187], v[50:53]
	v_mfma_f32_16x16x32_bf16 v[42:45], v[176:179], v[184:187], v[42:45]
	v_mfma_f32_16x16x32_bf16 v[34:37], v[168:171], v[192:195], v[34:37]
	v_mfma_f32_16x16x32_bf16 v[26:29], v[176:179], v[192:195], v[26:29]
	v_mfma_f32_16x16x32_bf16 v[18:21], v[168:171], v[206:209], v[18:21]
	v_mfma_f32_16x16x32_bf16 v[10:13], v[176:179], v[206:209], v[10:13]
	v_mfma_f32_16x16x32_bf16 v[6:9], v[168:171], v[214:217], v[6:9]
	v_mfma_f32_16x16x32_bf16 v[2:5], v[176:179], v[214:217], v[2:5]
	s_setprio 0
	s_barrier
	s_add_i32 s0, 0, 0x18000
	s_add_i32 s1, 0, 0x1c000
	v_add_u32_e32 v160, s0, v149
	v_add_u32_e32 v176, s1, v149
	ds_read_b128 v[142:145], v160
	ds_read_b128 v[152:155], v160 offset:1024
	ds_read_b128 v[156:159], v160 offset:2048
	ds_read_b128 v[160:163], v160 offset:3072
	ds_read_b128 v[164:167], v176
	ds_read_b128 v[168:171], v176 offset:1024
	ds_read_b128 v[172:175], v176 offset:2048
	ds_read_b128 v[176:179], v176 offset:3072
	s_add_u32 s62, s62, 0x80000
	s_addc_u32 s63, s63, 0
	s_mov_b32 m0, s29
	v_lshl_add_u64 v[224:225], s[62:63], 0, v[134:135]
	ds_read_b128 v[180:183], v151 offset:32768
	ds_read_b128 v[184:187], v151 offset:33792
	ds_read_b128 v[188:191], v151 offset:34816
	ds_read_b128 v[192:195], v151 offset:35840
	ds_read_b128 v[202:205], v151 offset:36864
	ds_read_b128 v[206:209], v151 offset:37888
	ds_read_b128 v[210:213], v151 offset:38912
	ds_read_b128 v[214:217], v151 offset:39936
	global_load_lds_dwordx4 v[224:225], off
	v_lshl_add_u64 v[224:225], s[62:63], 0, v[132:133]
	s_mov_b32 m0, s30
	s_nop 0
	global_load_lds_dwordx4 v[224:225], off
	s_waitcnt vmcnt(8)
	s_waitcnt lgkmcnt(0)
	s_barrier
	s_setprio 1
	s_waitcnt lgkmcnt(0)
	v_mfma_f32_16x16x32_bf16 v[126:129], v[142:145], v[180:183], v[126:129]
	v_mfma_f32_16x16x32_bf16 v[122:125], v[156:159], v[180:183], v[122:125]
	v_mfma_f32_16x16x32_bf16 v[118:121], v[142:145], v[188:191], v[118:121]
	v_mfma_f32_16x16x32_bf16 v[110:113], v[156:159], v[188:191], v[110:113]
	v_mfma_f32_16x16x32_bf16 v[102:105], v[142:145], v[202:205], v[102:105]
	v_mfma_f32_16x16x32_bf16 v[94:97], v[156:159], v[202:205], v[94:97]
	v_mfma_f32_16x16x32_bf16 v[86:89], v[142:145], v[210:213], v[86:89]
	v_mfma_f32_16x16x32_bf16 v[78:81], v[156:159], v[210:213], v[78:81]
	v_mfma_f32_16x16x32_bf16 v[126:129], v[152:155], v[184:187], v[126:129]
	v_mfma_f32_16x16x32_bf16 v[122:125], v[160:163], v[184:187], v[122:125]
	v_mfma_f32_16x16x32_bf16 v[118:121], v[152:155], v[192:195], v[118:121]
	v_mfma_f32_16x16x32_bf16 v[110:113], v[160:163], v[192:195], v[110:113]
	v_mfma_f32_16x16x32_bf16 v[102:105], v[152:155], v[206:209], v[102:105]
	v_mfma_f32_16x16x32_bf16 v[94:97], v[160:163], v[206:209], v[94:97]
	v_mfma_f32_16x16x32_bf16 v[86:89], v[152:155], v[214:217], v[86:89]
	v_mfma_f32_16x16x32_bf16 v[78:81], v[160:163], v[214:217], v[78:81]
	s_setprio 0
	s_setprio 1
	v_mfma_f32_16x16x32_bf16 v[114:117], v[164:167], v[180:183], v[114:117]
	v_mfma_f32_16x16x32_bf16 v[106:109], v[172:175], v[180:183], v[106:109]
	v_mfma_f32_16x16x32_bf16 v[98:101], v[164:167], v[188:191], v[98:101]
	v_mfma_f32_16x16x32_bf16 v[90:93], v[172:175], v[188:191], v[90:93]
	v_mfma_f32_16x16x32_bf16 v[82:85], v[164:167], v[202:205], v[82:85]
	v_mfma_f32_16x16x32_bf16 v[74:77], v[172:175], v[202:205], v[74:77]
	v_mfma_f32_16x16x32_bf16 v[70:73], v[164:167], v[210:213], v[70:73]
	v_mfma_f32_16x16x32_bf16 v[66:69], v[172:175], v[210:213], v[66:69]
	v_mfma_f32_16x16x32_bf16 v[114:117], v[168:171], v[184:187], v[114:117]
	v_mfma_f32_16x16x32_bf16 v[106:109], v[176:179], v[184:187], v[106:109]
	v_mfma_f32_16x16x32_bf16 v[98:101], v[168:171], v[192:195], v[98:101]
	v_mfma_f32_16x16x32_bf16 v[90:93], v[176:179], v[192:195], v[90:93]
	v_mfma_f32_16x16x32_bf16 v[82:85], v[168:171], v[206:209], v[82:85]
	v_mfma_f32_16x16x32_bf16 v[74:77], v[176:179], v[206:209], v[74:77]
	v_mfma_f32_16x16x32_bf16 v[70:73], v[168:171], v[214:217], v[70:73]
	v_mfma_f32_16x16x32_bf16 v[66:69], v[176:179], v[214:217], v[66:69]
	s_setprio 0
	s_barrier
	s_add_i32 s0, s0, s26
	v_lshl_add_u64 v[146:147], v[146:147], 0, s[16:17]
	s_mov_b32 m0, s0
	ds_read_b128 v[180:183], v151 offset:49152
	ds_read_b128 v[184:187], v151 offset:50176
	ds_read_b128 v[188:191], v151 offset:51200
	ds_read_b128 v[192:195], v151 offset:52224
	ds_read_b128 v[202:205], v151 offset:53248
	ds_read_b128 v[206:209], v151 offset:54272
	ds_read_b128 v[210:213], v151 offset:55296
	ds_read_b128 v[214:217], v151 offset:56320
	global_load_lds_dwordx4 v[146:147], off
	s_add_i32 m0, s0, 0x2000
	s_add_u32 s8, s8, 0x80080
	v_lshl_add_u64 v[146:147], v[218:219], 0, s[16:17]
	s_addc_u32 s9, s9, 0
	s_add_i32 s0, s1, s26
	global_load_lds_dwordx4 v[146:147], off
	v_lshl_add_u64 v[146:147], s[8:9], 0, v[196:197]
	s_mov_b32 m0, s0
	s_nop 0
	global_load_lds_dwordx4 v[146:147], off
	v_lshl_add_u64 v[146:147], s[8:9], 0, v[130:131]
	s_add_i32 m0, s0, 0x2000
	s_nop 0
	global_load_lds_dwordx4 v[146:147], off
	v_lshl_add_u64 v[146:147], v[220:221], 0, s[16:17]
	s_mov_b32 m0, s31
	s_nop 0
	global_load_lds_dwordx4 v[146:147], off
	v_lshl_add_u64 v[146:147], v[222:223], 0, s[16:17]
	s_mov_b32 m0, s34
	s_nop 0
	global_load_lds_dwordx4 v[146:147], off
	s_waitcnt vmcnt(8)
	s_waitcnt lgkmcnt(0)
	s_barrier
	s_setprio 1
	s_waitcnt lgkmcnt(0)
	v_mfma_f32_16x16x32_bf16 v[62:65], v[142:145], v[180:183], v[62:65]
	v_mfma_f32_16x16x32_bf16 v[58:61], v[156:159], v[180:183], v[58:61]
	v_mfma_f32_16x16x32_bf16 v[54:57], v[142:145], v[188:191], v[54:57]
	v_mfma_f32_16x16x32_bf16 v[46:49], v[156:159], v[188:191], v[46:49]
	v_mfma_f32_16x16x32_bf16 v[38:41], v[142:145], v[202:205], v[38:41]
	v_mfma_f32_16x16x32_bf16 v[30:33], v[156:159], v[202:205], v[30:33]
	v_mfma_f32_16x16x32_bf16 v[22:25], v[142:145], v[210:213], v[22:25]
	v_mfma_f32_16x16x32_bf16 v[14:17], v[156:159], v[210:213], v[14:17]
	v_mfma_f32_16x16x32_bf16 v[62:65], v[152:155], v[184:187], v[62:65]
	v_mfma_f32_16x16x32_bf16 v[58:61], v[160:163], v[184:187], v[58:61]
	v_mfma_f32_16x16x32_bf16 v[54:57], v[152:155], v[192:195], v[54:57]
	v_mfma_f32_16x16x32_bf16 v[46:49], v[160:163], v[192:195], v[46:49]
	v_mfma_f32_16x16x32_bf16 v[38:41], v[152:155], v[206:209], v[38:41]
	v_mfma_f32_16x16x32_bf16 v[30:33], v[160:163], v[206:209], v[30:33]
	v_mfma_f32_16x16x32_bf16 v[22:25], v[152:155], v[214:217], v[22:25]
	v_mfma_f32_16x16x32_bf16 v[14:17], v[160:163], v[214:217], v[14:17]
	s_setprio 0
	s_setprio 1
	v_mfma_f32_16x16x32_bf16 v[50:53], v[164:167], v[180:183], v[50:53]
	v_mfma_f32_16x16x32_bf16 v[42:45], v[172:175], v[180:183], v[42:45]
	v_mfma_f32_16x16x32_bf16 v[34:37], v[164:167], v[188:191], v[34:37]
	v_mfma_f32_16x16x32_bf16 v[26:29], v[172:175], v[188:191], v[26:29]
	v_mfma_f32_16x16x32_bf16 v[18:21], v[164:167], v[202:205], v[18:21]
	v_mfma_f32_16x16x32_bf16 v[10:13], v[172:175], v[202:205], v[10:13]
	v_mfma_f32_16x16x32_bf16 v[6:9], v[164:167], v[210:213], v[6:9]
	v_mfma_f32_16x16x32_bf16 v[2:5], v[172:175], v[210:213], v[2:5]
	v_mfma_f32_16x16x32_bf16 v[50:53], v[168:171], v[184:187], v[50:53]
	v_mfma_f32_16x16x32_bf16 v[42:45], v[176:179], v[184:187], v[42:45]
	v_mfma_f32_16x16x32_bf16 v[34:37], v[168:171], v[192:195], v[34:37]
	v_mfma_f32_16x16x32_bf16 v[26:29], v[176:179], v[192:195], v[26:29]
	v_mfma_f32_16x16x32_bf16 v[18:21], v[168:171], v[206:209], v[18:21]
	v_mfma_f32_16x16x32_bf16 v[10:13], v[176:179], v[206:209], v[10:13]
	v_mfma_f32_16x16x32_bf16 v[6:9], v[168:171], v[214:217], v[6:9]
	v_mfma_f32_16x16x32_bf16 v[2:5], v[176:179], v[214:217], v[2:5]
	s_add_u32 s69, s69, 0x100
	s_addc_u32 s70, s70, 0
	s_add_u32 s58, s58, 0x100
	s_addc_u32 s59, s59, 0
	s_cmp_ge_i32 s71, s64
	s_mov_b32 s8, s71
	s_setprio 0
	s_barrier
	s_cbranch_scc0 .LBB0_1135
	s_and_b64 vcc, exec, s[38:39]
	s_cbranch_vccz .LBB0_1138
	s_barrier

.LBB0_2239:
	s_add_i32 s73, s8, 2
	s_add_u32 s0, s44, 0xfff00080
	s_addc_u32 s1, s45, -1
	s_add_i32 s77, 0, 0x10000
	s_cmp_eq_u32 s70, s8
	s_cselect_b32 s67, s51, s1
	s_cselect_b32 s66, s53, s0
	s_cselect_b32 s9, s49, s72
	s_cselect_b32 s8, s69, s71
	s_add_i32 s78, 0, 0x14000
	v_add_u32_e32 v142, s77, v244
	v_add_u32_e32 v158, s78, v244
	ds_read_b128 v[130:133], v142
	ds_read_b128 v[134:137], v142 offset:1024
	ds_read_b128 v[138:141], v142 offset:2048
	ds_read_b128 v[142:145], v142 offset:3072
	ds_read_b128 v[146:149], v158
	ds_read_b128 v[150:153], v158 offset:1024
	ds_read_b128 v[154:157], v158 offset:2048
	ds_read_b128 v[158:161], v158 offset:3072
	v_lshl_add_u64 v[194:195], s[44:45], 0, v[210:211]
	s_add_i32 m0, s3, 0xc000
	ds_read_b128 v[162:165], v246
	ds_read_b128 v[166:169], v246 offset:1024
	ds_read_b128 v[170:173], v246 offset:2048
	ds_read_b128 v[174:177], v246 offset:3072
	ds_read_b128 v[178:181], v246 offset:4096
	ds_read_b128 v[182:185], v246 offset:5120
	ds_read_b128 v[186:189], v246 offset:6144
	ds_read_b128 v[190:193], v246 offset:7168
	global_load_lds_dwordx4 v[194:195], off
	v_lshl_add_u64 v[194:195], s[44:45], 0, v[208:209]
	s_add_i32 m0, s3, 0xe000
	s_nop 0
	global_load_lds_dwordx4 v[194:195], off
	s_waitcnt vmcnt(8)
	s_waitcnt lgkmcnt(0)
	s_barrier
	s_setprio 1
	s_waitcnt lgkmcnt(0)
	v_mfma_f32_16x16x32_bf16 v[126:129], v[130:133], v[162:165], v[126:129]
	v_mfma_f32_16x16x32_bf16 v[122:125], v[138:141], v[162:165], v[122:125]
	v_mfma_f32_16x16x32_bf16 v[110:113], v[130:133], v[170:173], v[110:113]
	v_mfma_f32_16x16x32_bf16 v[106:109], v[138:141], v[170:173], v[106:109]
	v_mfma_f32_16x16x32_bf16 v[94:97], v[130:133], v[178:181], v[94:97]
	v_mfma_f32_16x16x32_bf16 v[90:93], v[138:141], v[178:181], v[90:93]
	v_mfma_f32_16x16x32_bf16 v[78:81], v[130:133], v[186:189], v[78:81]
	v_mfma_f32_16x16x32_bf16 v[74:77], v[138:141], v[186:189], v[74:77]
	v_mfma_f32_16x16x32_bf16 v[126:129], v[134:137], v[166:169], v[126:129]
	v_mfma_f32_16x16x32_bf16 v[122:125], v[142:145], v[166:169], v[122:125]
	v_mfma_f32_16x16x32_bf16 v[110:113], v[134:137], v[174:177], v[110:113]
	v_mfma_f32_16x16x32_bf16 v[106:109], v[142:145], v[174:177], v[106:109]
	v_mfma_f32_16x16x32_bf16 v[94:97], v[134:137], v[182:185], v[94:97]
	v_mfma_f32_16x16x32_bf16 v[90:93], v[142:145], v[182:185], v[90:93]
	v_mfma_f32_16x16x32_bf16 v[78:81], v[134:137], v[190:193], v[78:81]
	v_mfma_f32_16x16x32_bf16 v[74:77], v[142:145], v[190:193], v[74:77]
	s_setprio 0
	s_setprio 1
	v_mfma_f32_16x16x32_bf16 v[118:121], v[146:149], v[162:165], v[118:121]
	v_mfma_f32_16x16x32_bf16 v[114:117], v[154:157], v[162:165], v[114:117]
	v_mfma_f32_16x16x32_bf16 v[102:105], v[146:149], v[170:173], v[102:105]
	v_mfma_f32_16x16x32_bf16 v[98:101], v[154:157], v[170:173], v[98:101]
	v_mfma_f32_16x16x32_bf16 v[86:89], v[146:149], v[178:181], v[86:89]
	v_mfma_f32_16x16x32_bf16 v[82:85], v[154:157], v[178:181], v[82:85]
	v_mfma_f32_16x16x32_bf16 v[70:73], v[146:149], v[186:189], v[70:73]
	v_mfma_f32_16x16x32_bf16 v[66:69], v[154:157], v[186:189], v[66:69]
	v_mfma_f32_16x16x32_bf16 v[118:121], v[150:153], v[166:169], v[118:121]
	v_mfma_f32_16x16x32_bf16 v[114:117], v[158:161], v[166:169], v[114:117]
	v_mfma_f32_16x16x32_bf16 v[102:105], v[150:153], v[174:177], v[102:105]
	v_mfma_f32_16x16x32_bf16 v[98:101], v[158:161], v[174:177], v[98:101]
	v_mfma_f32_16x16x32_bf16 v[86:89], v[150:153], v[182:185], v[86:89]
	v_mfma_f32_16x16x32_bf16 v[82:85], v[158:161], v[182:185], v[82:85]
	v_mfma_f32_16x16x32_bf16 v[70:73], v[150:153], v[190:193], v[70:73]
	v_mfma_f32_16x16x32_bf16 v[66:69], v[158:161], v[190:193], v[66:69]
	s_setprio 0
	s_barrier
	s_add_i32 s0, s77, s2
	v_lshl_add_u64 v[194:195], s[8:9], 0, v[196:197]
	s_mov_b32 m0, s0
	ds_read_b128 v[162:165], v246 offset:16384
	ds_read_b128 v[166:169], v246 offset:17408
	ds_read_b128 v[170:173], v246 offset:18432
	ds_read_b128 v[174:177], v246 offset:19456
	ds_read_b128 v[178:181], v246 offset:20480
	ds_read_b128 v[182:185], v246 offset:21504
	ds_read_b128 v[186:189], v246 offset:22528
	ds_read_b128 v[190:193], v246 offset:23552
	global_load_lds_dwordx4 v[194:195], off
	s_add_i32 m0, s0, 0x2000
	s_add_u32 s0, s8, 0x100000
	v_lshl_add_u64 v[212:213], s[8:9], 0, v[202:203]
	s_addc_u32 s1, s9, 0
	s_add_i32 s77, s78, s2
	global_load_lds_dwordx4 v[212:213], off
	v_lshl_add_u64 v[214:215], s[0:1], 0, v[196:197]
	s_mov_b32 m0, s77
	v_lshl_add_u64 v[216:217], s[66:67], 0, v[204:205]
	global_load_lds_dwordx4 v[214:215], off
	v_lshl_add_u64 v[214:215], s[0:1], 0, v[202:203]
	s_add_i32 m0, s77, 0x2000
	s_nop 0
	global_load_lds_dwordx4 v[214:215], off
	v_lshl_add_u64 v[214:215], s[66:67], 0, v[206:207]
	s_mov_b32 m0, s3
	s_nop 0
	global_load_lds_dwordx4 v[214:215], off
	s_mov_b32 m0, s10
	s_nop 0
	global_load_lds_dwordx4 v[216:217], off
	s_waitcnt vmcnt(8)
	s_waitcnt lgkmcnt(0)
	s_barrier
	s_setprio 1
	s_waitcnt lgkmcnt(0)
	v_mfma_f32_16x16x32_bf16 v[62:65], v[130:133], v[162:165], v[62:65]
	v_mfma_f32_16x16x32_bf16 v[58:61], v[138:141], v[162:165], v[58:61]
	v_mfma_f32_16x16x32_bf16 v[46:49], v[130:133], v[170:173], v[46:49]
	v_mfma_f32_16x16x32_bf16 v[42:45], v[138:141], v[170:173], v[42:45]
	v_mfma_f32_16x16x32_bf16 v[30:33], v[130:133], v[178:181], v[30:33]
	v_mfma_f32_16x16x32_bf16 v[26:29], v[138:141], v[178:181], v[26:29]
	v_mfma_f32_16x16x32_bf16 v[14:17], v[130:133], v[186:189], v[14:17]
	v_mfma_f32_16x16x32_bf16 v[10:13], v[138:141], v[186:189], v[10:13]
	v_mfma_f32_16x16x32_bf16 v[62:65], v[134:137], v[166:169], v[62:65]
	v_mfma_f32_16x16x32_bf16 v[58:61], v[142:145], v[166:169], v[58:61]
	v_mfma_f32_16x16x32_bf16 v[46:49], v[134:137], v[174:177], v[46:49]
	v_mfma_f32_16x16x32_bf16 v[42:45], v[142:145], v[174:177], v[42:45]
	v_mfma_f32_16x16x32_bf16 v[30:33], v[134:137], v[182:185], v[30:33]
	v_mfma_f32_16x16x32_bf16 v[26:29], v[142:145], v[182:185], v[26:29]
	v_mfma_f32_16x16x32_bf16 v[14:17], v[134:137], v[190:193], v[14:17]
	v_mfma_f32_16x16x32_bf16 v[10:13], v[142:145], v[190:193], v[10:13]
	s_setprio 0
	s_setprio 1
	v_mfma_f32_16x16x32_bf16 v[54:57], v[146:149], v[162:165], v[54:57]
	v_mfma_f32_16x16x32_bf16 v[50:53], v[154:157], v[162:165], v[50:53]
	v_mfma_f32_16x16x32_bf16 v[38:41], v[146:149], v[170:173], v[38:41]
	v_mfma_f32_16x16x32_bf16 v[34:37], v[154:157], v[170:173], v[34:37]
	v_mfma_f32_16x16x32_bf16 v[22:25], v[146:149], v[178:181], v[22:25]
	v_mfma_f32_16x16x32_bf16 v[18:21], v[154:157], v[178:181], v[18:21]
	v_mfma_f32_16x16x32_bf16 v[6:9], v[146:149], v[186:189], v[6:9]
	v_mfma_f32_16x16x32_bf16 v[2:5], v[154:157], v[186:189], v[2:5]
	v_mfma_f32_16x16x32_bf16 v[54:57], v[150:153], v[166:169], v[54:57]
	v_mfma_f32_16x16x32_bf16 v[50:53], v[158:161], v[166:169], v[50:53]
	v_mfma_f32_16x16x32_bf16 v[38:41], v[150:153], v[174:177], v[38:41]
	v_mfma_f32_16x16x32_bf16 v[34:37], v[158:161], v[174:177], v[34:37]
	v_mfma_f32_16x16x32_bf16 v[22:25], v[150:153], v[182:185], v[22:25]
	v_mfma_f32_16x16x32_bf16 v[18:21], v[158:161], v[182:185], v[18:21]
	v_mfma_f32_16x16x32_bf16 v[6:9], v[150:153], v[190:193], v[6:9]
	v_mfma_f32_16x16x32_bf16 v[2:5], v[158:161], v[190:193], v[2:5]
	s_setprio 0
	s_barrier
	s_add_i32 s77, 0, 0x18000
	s_add_i32 s78, 0, 0x1c000
	v_add_u32_e32 v142, s77, v244
	v_add_u32_e32 v158, s78, v244
	ds_read_b128 v[130:133], v142
	ds_read_b128 v[134:137], v142 offset:1024
	ds_read_b128 v[138:141], v142 offset:2048
	ds_read_b128 v[142:145], v142 offset:3072
	ds_read_b128 v[146:149], v158
	ds_read_b128 v[150:153], v158 offset:1024
	ds_read_b128 v[154:157], v158 offset:2048
	ds_read_b128 v[158:161], v158 offset:3072
	s_add_u32 s0, s66, 0x100000
	s_addc_u32 s1, s67, 0
	s_mov_b32 m0, s11
	v_lshl_add_u64 v[218:219], s[0:1], 0, v[206:207]
	ds_read_b128 v[162:165], v246 offset:32768
	ds_read_b128 v[166:169], v246 offset:33792
	ds_read_b128 v[170:173], v246 offset:34816
	ds_read_b128 v[174:177], v246 offset:35840
	ds_read_b128 v[178:181], v246 offset:36864
	ds_read_b128 v[182:185], v246 offset:37888
	ds_read_b128 v[186:189], v246 offset:38912
	ds_read_b128 v[190:193], v246 offset:39936
	global_load_lds_dwordx4 v[218:219], off
	v_lshl_add_u64 v[218:219], s[0:1], 0, v[204:205]
	s_mov_b32 m0, s26
	s_nop 0
	global_load_lds_dwordx4 v[218:219], off
	s_waitcnt vmcnt(8)
	s_waitcnt lgkmcnt(0)
	s_barrier
	s_setprio 1
	s_waitcnt lgkmcnt(0)
	v_mfma_f32_16x16x32_bf16 v[126:129], v[130:133], v[162:165], v[126:129]
	v_mfma_f32_16x16x32_bf16 v[122:125], v[138:141], v[162:165], v[122:125]
	v_mfma_f32_16x16x32_bf16 v[110:113], v[130:133], v[170:173], v[110:113]
	v_mfma_f32_16x16x32_bf16 v[106:109], v[138:141], v[170:173], v[106:109]
	v_mfma_f32_16x16x32_bf16 v[94:97], v[130:133], v[178:181], v[94:97]
	v_mfma_f32_16x16x32_bf16 v[90:93], v[138:141], v[178:181], v[90:93]
	v_mfma_f32_16x16x32_bf16 v[78:81], v[130:133], v[186:189], v[78:81]
	v_mfma_f32_16x16x32_bf16 v[74:77], v[138:141], v[186:189], v[74:77]
	v_mfma_f32_16x16x32_bf16 v[126:129], v[134:137], v[166:169], v[126:129]
	v_mfma_f32_16x16x32_bf16 v[122:125], v[142:145], v[166:169], v[122:125]
	v_mfma_f32_16x16x32_bf16 v[110:113], v[134:137], v[174:177], v[110:113]
	v_mfma_f32_16x16x32_bf16 v[106:109], v[142:145], v[174:177], v[106:109]
	v_mfma_f32_16x16x32_bf16 v[94:97], v[134:137], v[182:185], v[94:97]
	v_mfma_f32_16x16x32_bf16 v[90:93], v[142:145], v[182:185], v[90:93]
	v_mfma_f32_16x16x32_bf16 v[78:81], v[134:137], v[190:193], v[78:81]
	v_mfma_f32_16x16x32_bf16 v[74:77], v[142:145], v[190:193], v[74:77]
	s_setprio 0
	s_setprio 1
	v_mfma_f32_16x16x32_bf16 v[118:121], v[146:149], v[162:165], v[118:121]
	v_mfma_f32_16x16x32_bf16 v[114:117], v[154:157], v[162:165], v[114:117]
	v_mfma_f32_16x16x32_bf16 v[102:105], v[146:149], v[170:173], v[102:105]
	v_mfma_f32_16x16x32_bf16 v[98:101], v[154:157], v[170:173], v[98:101]
	v_mfma_f32_16x16x32_bf16 v[86:89], v[146:149], v[178:181], v[86:89]
	v_mfma_f32_16x16x32_bf16 v[82:85], v[154:157], v[178:181], v[82:85]
	v_mfma_f32_16x16x32_bf16 v[70:73], v[146:149], v[186:189], v[70:73]
	v_mfma_f32_16x16x32_bf16 v[66:69], v[154:157], v[186:189], v[66:69]
	v_mfma_f32_16x16x32_bf16 v[118:121], v[150:153], v[166:169], v[118:121]
	v_mfma_f32_16x16x32_bf16 v[114:117], v[158:161], v[166:169], v[114:117]
	v_mfma_f32_16x16x32_bf16 v[102:105], v[150:153], v[174:177], v[102:105]
	v_mfma_f32_16x16x32_bf16 v[98:101], v[158:161], v[174:177], v[98:101]
	v_mfma_f32_16x16x32_bf16 v[86:89], v[150:153], v[182:185], v[86:89]
	v_mfma_f32_16x16x32_bf16 v[82:85], v[158:161], v[182:185], v[82:85]
	v_mfma_f32_16x16x32_bf16 v[70:73], v[150:153], v[190:193], v[70:73]
	v_mfma_f32_16x16x32_bf16 v[66:69], v[158:161], v[190:193], v[66:69]
	s_setprio 0
	s_barrier
	s_add_i32 s0, s77, s2
	v_lshl_add_u64 v[194:195], v[194:195], 0, s[16:17]
	s_mov_b32 m0, s0
	ds_read_b128 v[162:165], v246 offset:49152
	ds_read_b128 v[166:169], v246 offset:50176
	ds_read_b128 v[170:173], v246 offset:51200
	ds_read_b128 v[174:177], v246 offset:52224
	ds_read_b128 v[178:181], v246 offset:53248
	ds_read_b128 v[182:185], v246 offset:54272
	ds_read_b128 v[186:189], v246 offset:55296
	ds_read_b128 v[190:193], v246 offset:56320
	global_load_lds_dwordx4 v[194:195], off
	s_add_i32 m0, s0, 0x2000
	s_add_u32 s0, s8, 0x100080
	v_lshl_add_u64 v[194:195], v[212:213], 0, s[16:17]
	s_addc_u32 s1, s9, 0
	s_add_i32 s8, s78, s2
	global_load_lds_dwordx4 v[194:195], off
	v_lshl_add_u64 v[194:195], s[0:1], 0, v[196:197]
	s_mov_b32 m0, s8
	s_nop 0
	global_load_lds_dwordx4 v[194:195], off
	v_lshl_add_u64 v[194:195], s[0:1], 0, v[202:203]
	s_add_i32 m0, s8, 0x2000
	s_nop 0
	global_load_lds_dwordx4 v[194:195], off
	v_lshl_add_u64 v[194:195], v[214:215], 0, s[16:17]
	s_mov_b32 m0, s27
	s_nop 0
	global_load_lds_dwordx4 v[194:195], off
	v_lshl_add_u64 v[194:195], v[216:217], 0, s[16:17]
	s_mov_b32 m0, s28
	s_nop 0
	global_load_lds_dwordx4 v[194:195], off
	s_waitcnt vmcnt(8)
	s_waitcnt lgkmcnt(0)
	s_barrier
	s_setprio 1
	s_waitcnt lgkmcnt(0)
	v_mfma_f32_16x16x32_bf16 v[62:65], v[130:133], v[162:165], v[62:65]
	v_mfma_f32_16x16x32_bf16 v[58:61], v[138:141], v[162:165], v[58:61]
	v_mfma_f32_16x16x32_bf16 v[46:49], v[130:133], v[170:173], v[46:49]
	v_mfma_f32_16x16x32_bf16 v[42:45], v[138:141], v[170:173], v[42:45]
	v_mfma_f32_16x16x32_bf16 v[30:33], v[130:133], v[178:181], v[30:33]
	v_mfma_f32_16x16x32_bf16 v[26:29], v[138:141], v[178:181], v[26:29]
	v_mfma_f32_16x16x32_bf16 v[14:17], v[130:133], v[186:189], v[14:17]
	v_mfma_f32_16x16x32_bf16 v[10:13], v[138:141], v[186:189], v[10:13]
	v_mfma_f32_16x16x32_bf16 v[62:65], v[134:137], v[166:169], v[62:65]
	v_mfma_f32_16x16x32_bf16 v[58:61], v[142:145], v[166:169], v[58:61]
	v_mfma_f32_16x16x32_bf16 v[46:49], v[134:137], v[174:177], v[46:49]
	v_mfma_f32_16x16x32_bf16 v[42:45], v[142:145], v[174:177], v[42:45]
	v_mfma_f32_16x16x32_bf16 v[30:33], v[134:137], v[182:185], v[30:33]
	v_mfma_f32_16x16x32_bf16 v[26:29], v[142:145], v[182:185], v[26:29]
	v_mfma_f32_16x16x32_bf16 v[14:17], v[134:137], v[190:193], v[14:17]
	v_mfma_f32_16x16x32_bf16 v[10:13], v[142:145], v[190:193], v[10:13]
	s_setprio 0
	s_setprio 1
	v_mfma_f32_16x16x32_bf16 v[54:57], v[146:149], v[162:165], v[54:57]
	v_mfma_f32_16x16x32_bf16 v[50:53], v[154:157], v[162:165], v[50:53]
	v_mfma_f32_16x16x32_bf16 v[38:41], v[146:149], v[170:173], v[38:41]
	v_mfma_f32_16x16x32_bf16 v[34:37], v[154:157], v[170:173], v[34:37]
	v_mfma_f32_16x16x32_bf16 v[22:25], v[146:149], v[178:181], v[22:25]
	v_mfma_f32_16x16x32_bf16 v[18:21], v[154:157], v[178:181], v[18:21]
	v_mfma_f32_16x16x32_bf16 v[6:9], v[146:149], v[186:189], v[6:9]
	v_mfma_f32_16x16x32_bf16 v[2:5], v[154:157], v[186:189], v[2:5]
	v_mfma_f32_16x16x32_bf16 v[54:57], v[150:153], v[166:169], v[54:57]
	v_mfma_f32_16x16x32_bf16 v[50:53], v[158:161], v[166:169], v[50:53]
	v_mfma_f32_16x16x32_bf16 v[38:41], v[150:153], v[174:177], v[38:41]
	v_mfma_f32_16x16x32_bf16 v[34:37], v[158:161], v[174:177], v[34:37]
	v_mfma_f32_16x16x32_bf16 v[22:25], v[150:153], v[182:185], v[22:25]
	v_mfma_f32_16x16x32_bf16 v[18:21], v[158:161], v[182:185], v[18:21]
	v_mfma_f32_16x16x32_bf16 v[6:9], v[150:153], v[190:193], v[6:9]
	v_mfma_f32_16x16x32_bf16 v[2:5], v[158:161], v[190:193], v[2:5]
	s_add_u32 s71, s71, 0x100
	s_addc_u32 s72, s72, 0
	s_add_u32 s44, s44, 0x100
	s_addc_u32 s45, s45, 0
	s_cmp_ge_i32 s73, s35
	s_mov_b32 s8, s73
	s_setprio 0
	s_barrier
	s_cbranch_scc0 .LBB0_2239
	s_and_b64 vcc, exec, s[46:47]
	s_cbranch_vccz .LBB0_2242
	s_barrier

.LBB0_2357:
	s_add_i32 s77, s8, 2
	s_add_u32 s0, s62, 0xfff80080
	s_addc_u32 s1, s63, -1
	s_add_i32 s78, 0, 0x10000
	s_cmp_eq_u32 s71, s8
	s_cselect_b32 s65, s41, s1
	s_cselect_b32 s64, s45, s0
	s_cselect_b32 s9, s43, s73
	s_cselect_b32 s8, s70, s72
	s_add_i32 s79, 0, 0x14000
	v_add_u32_e32 v142, s78, v188
	v_add_u32_e32 v158, s79, v188
	ds_read_b128 v[130:133], v142
	ds_read_b128 v[134:137], v142 offset:1024
	ds_read_b128 v[138:141], v142 offset:2048
	ds_read_b128 v[142:145], v142 offset:3072
	ds_read_b128 v[146:149], v158
	ds_read_b128 v[150:153], v158 offset:1024
	ds_read_b128 v[154:157], v158 offset:2048
	ds_read_b128 v[158:161], v158 offset:3072
	v_lshl_add_u64 v[194:195], s[62:63], 0, v[178:179]
	s_add_i32 m0, s27, 0xc000
	ds_read_b128 v[162:165], v189
	ds_read_b128 v[180:183], v189 offset:1024
	ds_read_b128 v[184:187], v189 offset:2048
	ds_read_b128 v[190:193], v189 offset:3072
	ds_read_b128 v[202:205], v189 offset:4096
	ds_read_b128 v[206:209], v189 offset:5120
	ds_read_b128 v[210:213], v189 offset:6144
	ds_read_b128 v[214:217], v189 offset:7168
	global_load_lds_dwordx4 v[194:195], off
	v_lshl_add_u64 v[194:195], s[62:63], 0, v[176:177]
	s_add_i32 m0, s27, 0xe000
	s_nop 0
	global_load_lds_dwordx4 v[194:195], off
	s_waitcnt vmcnt(8)
	s_waitcnt lgkmcnt(0)
	s_barrier
	s_setprio 1
	s_waitcnt lgkmcnt(0)
	v_mfma_f32_16x16x32_bf16 v[126:129], v[130:133], v[162:165], v[126:129]
	v_mfma_f32_16x16x32_bf16 v[122:125], v[138:141], v[162:165], v[122:125]
	v_mfma_f32_16x16x32_bf16 v[110:113], v[130:133], v[184:187], v[110:113]
	v_mfma_f32_16x16x32_bf16 v[106:109], v[138:141], v[184:187], v[106:109]
	v_mfma_f32_16x16x32_bf16 v[98:101], v[130:133], v[202:205], v[98:101]
	v_mfma_f32_16x16x32_bf16 v[90:93], v[138:141], v[202:205], v[90:93]
	v_mfma_f32_16x16x32_bf16 v[82:85], v[130:133], v[210:213], v[82:85]
	v_mfma_f32_16x16x32_bf16 v[74:77], v[138:141], v[210:213], v[74:77]
	v_mfma_f32_16x16x32_bf16 v[126:129], v[134:137], v[180:183], v[126:129]
	v_mfma_f32_16x16x32_bf16 v[122:125], v[142:145], v[180:183], v[122:125]
	v_mfma_f32_16x16x32_bf16 v[110:113], v[134:137], v[190:193], v[110:113]
	v_mfma_f32_16x16x32_bf16 v[106:109], v[142:145], v[190:193], v[106:109]
	v_mfma_f32_16x16x32_bf16 v[98:101], v[134:137], v[206:209], v[98:101]
	v_mfma_f32_16x16x32_bf16 v[90:93], v[142:145], v[206:209], v[90:93]
	v_mfma_f32_16x16x32_bf16 v[82:85], v[134:137], v[214:217], v[82:85]
	v_mfma_f32_16x16x32_bf16 v[74:77], v[142:145], v[214:217], v[74:77]
	s_setprio 0
	s_setprio 1
	v_mfma_f32_16x16x32_bf16 v[118:121], v[146:149], v[162:165], v[118:121]
	v_mfma_f32_16x16x32_bf16 v[114:117], v[154:157], v[162:165], v[114:117]
	v_mfma_f32_16x16x32_bf16 v[102:105], v[146:149], v[184:187], v[102:105]
	v_mfma_f32_16x16x32_bf16 v[94:97], v[154:157], v[184:187], v[94:97]
	v_mfma_f32_16x16x32_bf16 v[86:89], v[146:149], v[202:205], v[86:89]
	v_mfma_f32_16x16x32_bf16 v[78:81], v[154:157], v[202:205], v[78:81]
	v_mfma_f32_16x16x32_bf16 v[70:73], v[146:149], v[210:213], v[70:73]
	v_mfma_f32_16x16x32_bf16 v[66:69], v[154:157], v[210:213], v[66:69]
	v_mfma_f32_16x16x32_bf16 v[118:121], v[150:153], v[180:183], v[118:121]
	v_mfma_f32_16x16x32_bf16 v[114:117], v[158:161], v[180:183], v[114:117]
	v_mfma_f32_16x16x32_bf16 v[102:105], v[150:153], v[190:193], v[102:105]
	v_mfma_f32_16x16x32_bf16 v[94:97], v[158:161], v[190:193], v[94:97]
	v_mfma_f32_16x16x32_bf16 v[86:89], v[150:153], v[206:209], v[86:89]
	v_mfma_f32_16x16x32_bf16 v[78:81], v[158:161], v[206:209], v[78:81]
	v_mfma_f32_16x16x32_bf16 v[70:73], v[150:153], v[214:217], v[70:73]
	v_mfma_f32_16x16x32_bf16 v[66:69], v[158:161], v[214:217], v[66:69]
	s_setprio 0
	s_barrier
	s_add_i32 s0, s78, s26
	v_lshl_add_u64 v[194:195], s[8:9], 0, v[196:197]
	s_mov_b32 m0, s0
	ds_read_b128 v[162:165], v189 offset:16384
	ds_read_b128 v[180:183], v189 offset:17408
	ds_read_b128 v[184:187], v189 offset:18432
	ds_read_b128 v[190:193], v189 offset:19456
	ds_read_b128 v[202:205], v189 offset:20480
	ds_read_b128 v[206:209], v189 offset:21504
	ds_read_b128 v[210:213], v189 offset:22528
	ds_read_b128 v[214:217], v189 offset:23552
	global_load_lds_dwordx4 v[194:195], off
	s_add_i32 m0, s0, 0x2000
	s_add_u32 s0, s8, 0x80000
	v_lshl_add_u64 v[218:219], s[8:9], 0, v[170:171]
	s_addc_u32 s1, s9, 0
	s_add_i32 s78, s79, s26
	global_load_lds_dwordx4 v[218:219], off
	v_lshl_add_u64 v[220:221], s[0:1], 0, v[196:197]
	s_mov_b32 m0, s78
	v_lshl_add_u64 v[222:223], s[64:65], 0, v[168:169]
	global_load_lds_dwordx4 v[220:221], off
	v_lshl_add_u64 v[220:221], s[0:1], 0, v[170:171]
	s_add_i32 m0, s78, 0x2000
	s_nop 0
	global_load_lds_dwordx4 v[220:221], off
	v_lshl_add_u64 v[220:221], s[64:65], 0, v[166:167]
	s_mov_b32 m0, s27
	s_nop 0
	global_load_lds_dwordx4 v[220:221], off
	s_mov_b32 m0, s28
	s_nop 0
	global_load_lds_dwordx4 v[222:223], off
	s_waitcnt vmcnt(8)
	s_waitcnt lgkmcnt(0)
	s_barrier
	s_setprio 1
	s_waitcnt lgkmcnt(0)
	v_mfma_f32_16x16x32_bf16 v[62:65], v[130:133], v[162:165], v[62:65]
	v_mfma_f32_16x16x32_bf16 v[58:61], v[138:141], v[162:165], v[58:61]
	v_mfma_f32_16x16x32_bf16 v[50:53], v[130:133], v[184:187], v[50:53]
	v_mfma_f32_16x16x32_bf16 v[42:45], v[138:141], v[184:187], v[42:45]
	v_mfma_f32_16x16x32_bf16 v[34:37], v[130:133], v[202:205], v[34:37]
	v_mfma_f32_16x16x32_bf16 v[26:29], v[138:141], v[202:205], v[26:29]
	v_mfma_f32_16x16x32_bf16 v[18:21], v[130:133], v[210:213], v[18:21]
	v_mfma_f32_16x16x32_bf16 v[10:13], v[138:141], v[210:213], v[10:13]
	v_mfma_f32_16x16x32_bf16 v[62:65], v[134:137], v[180:183], v[62:65]
	v_mfma_f32_16x16x32_bf16 v[58:61], v[142:145], v[180:183], v[58:61]
	v_mfma_f32_16x16x32_bf16 v[50:53], v[134:137], v[190:193], v[50:53]
	v_mfma_f32_16x16x32_bf16 v[42:45], v[142:145], v[190:193], v[42:45]
	v_mfma_f32_16x16x32_bf16 v[34:37], v[134:137], v[206:209], v[34:37]
	v_mfma_f32_16x16x32_bf16 v[26:29], v[142:145], v[206:209], v[26:29]
	v_mfma_f32_16x16x32_bf16 v[18:21], v[134:137], v[214:217], v[18:21]
	v_mfma_f32_16x16x32_bf16 v[10:13], v[142:145], v[214:217], v[10:13]
	s_setprio 0
	s_setprio 1
	v_mfma_f32_16x16x32_bf16 v[54:57], v[146:149], v[162:165], v[54:57]
	v_mfma_f32_16x16x32_bf16 v[46:49], v[154:157], v[162:165], v[46:49]
	v_mfma_f32_16x16x32_bf16 v[38:41], v[146:149], v[184:187], v[38:41]
	v_mfma_f32_16x16x32_bf16 v[30:33], v[154:157], v[184:187], v[30:33]
	v_mfma_f32_16x16x32_bf16 v[22:25], v[146:149], v[202:205], v[22:25]
	v_mfma_f32_16x16x32_bf16 v[14:17], v[154:157], v[202:205], v[14:17]
	v_mfma_f32_16x16x32_bf16 v[6:9], v[146:149], v[210:213], v[6:9]
	v_mfma_f32_16x16x32_bf16 v[2:5], v[154:157], v[210:213], v[2:5]
	v_mfma_f32_16x16x32_bf16 v[54:57], v[150:153], v[180:183], v[54:57]
	v_mfma_f32_16x16x32_bf16 v[46:49], v[158:161], v[180:183], v[46:49]
	v_mfma_f32_16x16x32_bf16 v[38:41], v[150:153], v[190:193], v[38:41]
	v_mfma_f32_16x16x32_bf16 v[30:33], v[158:161], v[190:193], v[30:33]
	v_mfma_f32_16x16x32_bf16 v[22:25], v[150:153], v[206:209], v[22:25]
	v_mfma_f32_16x16x32_bf16 v[14:17], v[158:161], v[206:209], v[14:17]
	v_mfma_f32_16x16x32_bf16 v[6:9], v[150:153], v[214:217], v[6:9]
	v_mfma_f32_16x16x32_bf16 v[2:5], v[158:161], v[214:217], v[2:5]
	s_setprio 0
	s_barrier
	s_add_i32 s78, 0, 0x18000
	s_add_i32 s79, 0, 0x1c000
	v_add_u32_e32 v142, s78, v188
	v_add_u32_e32 v158, s79, v188
	ds_read_b128 v[130:133], v142
	ds_read_b128 v[134:137], v142 offset:1024
	ds_read_b128 v[138:141], v142 offset:2048
	ds_read_b128 v[142:145], v142 offset:3072
	ds_read_b128 v[146:149], v158
	ds_read_b128 v[150:153], v158 offset:1024
	ds_read_b128 v[154:157], v158 offset:2048
	ds_read_b128 v[158:161], v158 offset:3072
	s_add_u32 s0, s64, 0x80000
	s_addc_u32 s1, s65, 0
	s_mov_b32 m0, s29
	v_lshl_add_u64 v[224:225], s[0:1], 0, v[166:167]
	ds_read_b128 v[162:165], v189 offset:32768
	ds_read_b128 v[180:183], v189 offset:33792
	ds_read_b128 v[184:187], v189 offset:34816
	ds_read_b128 v[190:193], v189 offset:35840
	ds_read_b128 v[202:205], v189 offset:36864
	ds_read_b128 v[206:209], v189 offset:37888
	ds_read_b128 v[210:213], v189 offset:38912
	ds_read_b128 v[214:217], v189 offset:39936
	global_load_lds_dwordx4 v[224:225], off
	v_lshl_add_u64 v[224:225], s[0:1], 0, v[168:169]
	s_mov_b32 m0, s30
	s_nop 0
	global_load_lds_dwordx4 v[224:225], off
	s_waitcnt vmcnt(8)
	s_waitcnt lgkmcnt(0)
	s_barrier
	s_setprio 1
	s_waitcnt lgkmcnt(0)
	v_mfma_f32_16x16x32_bf16 v[126:129], v[130:133], v[162:165], v[126:129]
	v_mfma_f32_16x16x32_bf16 v[122:125], v[138:141], v[162:165], v[122:125]
	v_mfma_f32_16x16x32_bf16 v[110:113], v[130:133], v[184:187], v[110:113]
	v_mfma_f32_16x16x32_bf16 v[106:109], v[138:141], v[184:187], v[106:109]
	v_mfma_f32_16x16x32_bf16 v[98:101], v[130:133], v[202:205], v[98:101]
	v_mfma_f32_16x16x32_bf16 v[90:93], v[138:141], v[202:205], v[90:93]
	v_mfma_f32_16x16x32_bf16 v[82:85], v[130:133], v[210:213], v[82:85]
	v_mfma_f32_16x16x32_bf16 v[74:77], v[138:141], v[210:213], v[74:77]
	v_mfma_f32_16x16x32_bf16 v[126:129], v[134:137], v[180:183], v[126:129]
	v_mfma_f32_16x16x32_bf16 v[122:125], v[142:145], v[180:183], v[122:125]
	v_mfma_f32_16x16x32_bf16 v[110:113], v[134:137], v[190:193], v[110:113]
	v_mfma_f32_16x16x32_bf16 v[106:109], v[142:145], v[190:193], v[106:109]
	v_mfma_f32_16x16x32_bf16 v[98:101], v[134:137], v[206:209], v[98:101]
	v_mfma_f32_16x16x32_bf16 v[90:93], v[142:145], v[206:209], v[90:93]
	v_mfma_f32_16x16x32_bf16 v[82:85], v[134:137], v[214:217], v[82:85]
	v_mfma_f32_16x16x32_bf16 v[74:77], v[142:145], v[214:217], v[74:77]
	s_setprio 0
	s_setprio 1
	v_mfma_f32_16x16x32_bf16 v[118:121], v[146:149], v[162:165], v[118:121]
	v_mfma_f32_16x16x32_bf16 v[114:117], v[154:157], v[162:165], v[114:117]
	v_mfma_f32_16x16x32_bf16 v[102:105], v[146:149], v[184:187], v[102:105]
	v_mfma_f32_16x16x32_bf16 v[94:97], v[154:157], v[184:187], v[94:97]
	v_mfma_f32_16x16x32_bf16 v[86:89], v[146:149], v[202:205], v[86:89]
	v_mfma_f32_16x16x32_bf16 v[78:81], v[154:157], v[202:205], v[78:81]
	v_mfma_f32_16x16x32_bf16 v[70:73], v[146:149], v[210:213], v[70:73]
	v_mfma_f32_16x16x32_bf16 v[66:69], v[154:157], v[210:213], v[66:69]
	v_mfma_f32_16x16x32_bf16 v[118:121], v[150:153], v[180:183], v[118:121]
	v_mfma_f32_16x16x32_bf16 v[114:117], v[158:161], v[180:183], v[114:117]
	v_mfma_f32_16x16x32_bf16 v[102:105], v[150:153], v[190:193], v[102:105]
	v_mfma_f32_16x16x32_bf16 v[94:97], v[158:161], v[190:193], v[94:97]
	v_mfma_f32_16x16x32_bf16 v[86:89], v[150:153], v[206:209], v[86:89]
	v_mfma_f32_16x16x32_bf16 v[78:81], v[158:161], v[206:209], v[78:81]
	v_mfma_f32_16x16x32_bf16 v[70:73], v[150:153], v[214:217], v[70:73]
	v_mfma_f32_16x16x32_bf16 v[66:69], v[158:161], v[214:217], v[66:69]
	s_setprio 0
	s_barrier
	s_add_i32 s0, s78, s26
	v_lshl_add_u64 v[194:195], v[194:195], 0, s[16:17]
	s_mov_b32 m0, s0
	ds_read_b128 v[162:165], v189 offset:49152
	ds_read_b128 v[180:183], v189 offset:50176
	ds_read_b128 v[184:187], v189 offset:51200
	ds_read_b128 v[190:193], v189 offset:52224
	ds_read_b128 v[202:205], v189 offset:53248
	ds_read_b128 v[206:209], v189 offset:54272
	ds_read_b128 v[210:213], v189 offset:55296
	ds_read_b128 v[214:217], v189 offset:56320
	global_load_lds_dwordx4 v[194:195], off
	s_add_i32 m0, s0, 0x2000
	s_add_u32 s0, s8, 0x80080
	v_lshl_add_u64 v[194:195], v[218:219], 0, s[16:17]
	s_addc_u32 s1, s9, 0
	s_add_i32 s8, s79, s26
	global_load_lds_dwordx4 v[194:195], off
	v_lshl_add_u64 v[194:195], s[0:1], 0, v[196:197]
	s_mov_b32 m0, s8
	s_nop 0
	global_load_lds_dwordx4 v[194:195], off
	v_lshl_add_u64 v[194:195], s[0:1], 0, v[170:171]
	s_add_i32 m0, s8, 0x2000
	s_nop 0
	global_load_lds_dwordx4 v[194:195], off
	v_lshl_add_u64 v[194:195], v[220:221], 0, s[16:17]
	s_mov_b32 m0, s35
	s_nop 0
	global_load_lds_dwordx4 v[194:195], off
	v_lshl_add_u64 v[194:195], v[222:223], 0, s[16:17]
	s_mov_b32 m0, s53
	s_nop 0
	global_load_lds_dwordx4 v[194:195], off
	s_waitcnt vmcnt(8)
	s_waitcnt lgkmcnt(0)
	s_barrier
	s_setprio 1
	s_waitcnt lgkmcnt(0)
	v_mfma_f32_16x16x32_bf16 v[62:65], v[130:133], v[162:165], v[62:65]
	v_mfma_f32_16x16x32_bf16 v[58:61], v[138:141], v[162:165], v[58:61]
	v_mfma_f32_16x16x32_bf16 v[50:53], v[130:133], v[184:187], v[50:53]
	v_mfma_f32_16x16x32_bf16 v[42:45], v[138:141], v[184:187], v[42:45]
	v_mfma_f32_16x16x32_bf16 v[34:37], v[130:133], v[202:205], v[34:37]
	v_mfma_f32_16x16x32_bf16 v[26:29], v[138:141], v[202:205], v[26:29]
	v_mfma_f32_16x16x32_bf16 v[18:21], v[130:133], v[210:213], v[18:21]
	v_mfma_f32_16x16x32_bf16 v[10:13], v[138:141], v[210:213], v[10:13]
	v_mfma_f32_16x16x32_bf16 v[62:65], v[134:137], v[180:183], v[62:65]
	v_mfma_f32_16x16x32_bf16 v[58:61], v[142:145], v[180:183], v[58:61]
	v_mfma_f32_16x16x32_bf16 v[50:53], v[134:137], v[190:193], v[50:53]
	v_mfma_f32_16x16x32_bf16 v[42:45], v[142:145], v[190:193], v[42:45]
	v_mfma_f32_16x16x32_bf16 v[34:37], v[134:137], v[206:209], v[34:37]
	v_mfma_f32_16x16x32_bf16 v[26:29], v[142:145], v[206:209], v[26:29]
	v_mfma_f32_16x16x32_bf16 v[18:21], v[134:137], v[214:217], v[18:21]
	v_mfma_f32_16x16x32_bf16 v[10:13], v[142:145], v[214:217], v[10:13]
	s_setprio 0
	s_setprio 1
	v_mfma_f32_16x16x32_bf16 v[54:57], v[146:149], v[162:165], v[54:57]
	v_mfma_f32_16x16x32_bf16 v[46:49], v[154:157], v[162:165], v[46:49]
	v_mfma_f32_16x16x32_bf16 v[38:41], v[146:149], v[184:187], v[38:41]
	v_mfma_f32_16x16x32_bf16 v[30:33], v[154:157], v[184:187], v[30:33]
	v_mfma_f32_16x16x32_bf16 v[22:25], v[146:149], v[202:205], v[22:25]
	v_mfma_f32_16x16x32_bf16 v[14:17], v[154:157], v[202:205], v[14:17]
	v_mfma_f32_16x16x32_bf16 v[6:9], v[146:149], v[210:213], v[6:9]
	v_mfma_f32_16x16x32_bf16 v[2:5], v[154:157], v[210:213], v[2:5]
	v_mfma_f32_16x16x32_bf16 v[54:57], v[150:153], v[180:183], v[54:57]
	v_mfma_f32_16x16x32_bf16 v[46:49], v[158:161], v[180:183], v[46:49]
	v_mfma_f32_16x16x32_bf16 v[38:41], v[150:153], v[190:193], v[38:41]
	v_mfma_f32_16x16x32_bf16 v[30:33], v[158:161], v[190:193], v[30:33]
	v_mfma_f32_16x16x32_bf16 v[22:25], v[150:153], v[206:209], v[22:25]
	v_mfma_f32_16x16x32_bf16 v[14:17], v[158:161], v[206:209], v[14:17]
	v_mfma_f32_16x16x32_bf16 v[6:9], v[150:153], v[214:217], v[6:9]
	v_mfma_f32_16x16x32_bf16 v[2:5], v[158:161], v[214:217], v[2:5]
	s_add_u32 s72, s72, 0x100
	s_addc_u32 s73, s73, 0
	s_add_u32 s62, s62, 0x100
	s_addc_u32 s63, s63, 0
	s_cmp_ge_i32 s77, s69
	s_mov_b32 s8, s77
	s_setprio 0
	s_barrier
	s_cbranch_scc0 .LBB0_2357
	s_and_b64 vcc, exec, s[38:39]
	s_cbranch_vccz .LBB0_2360
	s_barrier

.LBB0_2507:
	s_add_i32 s69, s8, 2
	s_add_u32 s0, s52, 0xfff80080
	s_addc_u32 s1, s53, -1
	s_add_i32 s70, 0, 0x10000
	s_cmp_eq_u32 s66, s8
	s_cselect_b32 s59, s41, s1
	s_cselect_b32 s58, s45, s0
	s_cselect_b32 s9, s43, s68
	s_cselect_b32 s8, s65, s67
	s_add_i32 s71, 0, 0x14000
	v_add_u32_e32 v156, s70, v141
	v_add_u32_e32 v172, s71, v141
	ds_read_b128 v[144:147], v156
	ds_read_b128 v[148:151], v156 offset:1024
	ds_read_b128 v[152:155], v156 offset:2048
	ds_read_b128 v[156:159], v156 offset:3072
	ds_read_b128 v[160:163], v172
	ds_read_b128 v[164:167], v172 offset:1024
	ds_read_b128 v[168:171], v172 offset:2048
	ds_read_b128 v[172:175], v172 offset:3072
	v_lshl_add_u64 v[214:215], s[52:53], 0, v[138:139]
	s_add_i32 m0, s27, 0xc000
	ds_read_b128 v[176:179], v143
	ds_read_b128 v[180:183], v143 offset:1024
	ds_read_b128 v[184:187], v143 offset:2048
	ds_read_b128 v[188:191], v143 offset:3072
	ds_read_b128 v[192:195], v143 offset:4096
	ds_read_b128 v[202:205], v143 offset:5120
	ds_read_b128 v[206:209], v143 offset:6144
	ds_read_b128 v[210:213], v143 offset:7168
	global_load_lds_dwordx4 v[214:215], off
	v_lshl_add_u64 v[214:215], s[52:53], 0, v[136:137]
	s_add_i32 m0, s27, 0xe000
	s_nop 0
	global_load_lds_dwordx4 v[214:215], off
	s_waitcnt vmcnt(8)
	s_waitcnt lgkmcnt(0)
	s_barrier
	s_setprio 1
	s_waitcnt lgkmcnt(0)
	v_mfma_f32_16x16x32_bf16 v[126:129], v[144:147], v[176:179], v[126:129]
	v_mfma_f32_16x16x32_bf16 v[118:121], v[152:155], v[176:179], v[118:121]
	v_mfma_f32_16x16x32_bf16 v[110:113], v[144:147], v[184:187], v[110:113]
	v_mfma_f32_16x16x32_bf16 v[102:105], v[152:155], v[184:187], v[102:105]
	v_mfma_f32_16x16x32_bf16 v[94:97], v[144:147], v[192:195], v[94:97]
	v_mfma_f32_16x16x32_bf16 v[86:89], v[152:155], v[192:195], v[86:89]
	v_mfma_f32_16x16x32_bf16 v[78:81], v[144:147], v[206:209], v[78:81]
	v_mfma_f32_16x16x32_bf16 v[70:73], v[152:155], v[206:209], v[70:73]
	v_mfma_f32_16x16x32_bf16 v[126:129], v[148:151], v[180:183], v[126:129]
	v_mfma_f32_16x16x32_bf16 v[118:121], v[156:159], v[180:183], v[118:121]
	v_mfma_f32_16x16x32_bf16 v[110:113], v[148:151], v[188:191], v[110:113]
	v_mfma_f32_16x16x32_bf16 v[102:105], v[156:159], v[188:191], v[102:105]
	v_mfma_f32_16x16x32_bf16 v[94:97], v[148:151], v[202:205], v[94:97]
	v_mfma_f32_16x16x32_bf16 v[86:89], v[156:159], v[202:205], v[86:89]
	v_mfma_f32_16x16x32_bf16 v[78:81], v[148:151], v[210:213], v[78:81]
	v_mfma_f32_16x16x32_bf16 v[70:73], v[156:159], v[210:213], v[70:73]
	s_setprio 0
	s_setprio 1
	v_mfma_f32_16x16x32_bf16 v[122:125], v[160:163], v[176:179], v[122:125]
	v_mfma_f32_16x16x32_bf16 v[114:117], v[168:171], v[176:179], v[114:117]
	v_mfma_f32_16x16x32_bf16 v[106:109], v[160:163], v[184:187], v[106:109]
	v_mfma_f32_16x16x32_bf16 v[98:101], v[168:171], v[184:187], v[98:101]
	v_mfma_f32_16x16x32_bf16 v[90:93], v[160:163], v[192:195], v[90:93]
	v_mfma_f32_16x16x32_bf16 v[82:85], v[168:171], v[192:195], v[82:85]
	v_mfma_f32_16x16x32_bf16 v[74:77], v[160:163], v[206:209], v[74:77]
	v_mfma_f32_16x16x32_bf16 v[66:69], v[168:171], v[206:209], v[66:69]
	v_mfma_f32_16x16x32_bf16 v[122:125], v[164:167], v[180:183], v[122:125]
	v_mfma_f32_16x16x32_bf16 v[114:117], v[172:175], v[180:183], v[114:117]
	v_mfma_f32_16x16x32_bf16 v[106:109], v[164:167], v[188:191], v[106:109]
	v_mfma_f32_16x16x32_bf16 v[98:101], v[172:175], v[188:191], v[98:101]
	v_mfma_f32_16x16x32_bf16 v[90:93], v[164:167], v[202:205], v[90:93]
	v_mfma_f32_16x16x32_bf16 v[82:85], v[172:175], v[202:205], v[82:85]
	v_mfma_f32_16x16x32_bf16 v[74:77], v[164:167], v[210:213], v[74:77]
	v_mfma_f32_16x16x32_bf16 v[66:69], v[172:175], v[210:213], v[66:69]
	s_setprio 0
	s_barrier
	s_add_i32 s0, s70, s26
	v_lshl_add_u64 v[214:215], s[8:9], 0, v[196:197]
	s_mov_b32 m0, s0
	ds_read_b128 v[176:179], v143 offset:16384
	ds_read_b128 v[180:183], v143 offset:17408
	ds_read_b128 v[184:187], v143 offset:18432
	ds_read_b128 v[188:191], v143 offset:19456
	ds_read_b128 v[192:195], v143 offset:20480
	ds_read_b128 v[202:205], v143 offset:21504
	ds_read_b128 v[206:209], v143 offset:22528
	ds_read_b128 v[210:213], v143 offset:23552
	global_load_lds_dwordx4 v[214:215], off
	s_add_i32 m0, s0, 0x2000
	s_add_u32 s0, s8, 0x80000
	v_lshl_add_u64 v[216:217], s[8:9], 0, v[130:131]
	s_addc_u32 s1, s9, 0
	s_add_i32 s70, s71, s26
	global_load_lds_dwordx4 v[216:217], off
	v_lshl_add_u64 v[218:219], s[0:1], 0, v[196:197]
	s_mov_b32 m0, s70
	v_lshl_add_u64 v[220:221], s[58:59], 0, v[132:133]
	global_load_lds_dwordx4 v[218:219], off
	v_lshl_add_u64 v[218:219], s[0:1], 0, v[130:131]
	s_add_i32 m0, s70, 0x2000
	s_nop 0
	global_load_lds_dwordx4 v[218:219], off
	v_lshl_add_u64 v[218:219], s[58:59], 0, v[134:135]
	s_mov_b32 m0, s27
	s_nop 0
	global_load_lds_dwordx4 v[218:219], off
	s_mov_b32 m0, s28
	s_nop 0
	global_load_lds_dwordx4 v[220:221], off
	s_waitcnt vmcnt(8)
	s_waitcnt lgkmcnt(0)
	s_barrier
	s_setprio 1
	s_waitcnt lgkmcnt(0)
	v_mfma_f32_16x16x32_bf16 v[62:65], v[144:147], v[176:179], v[62:65]
	v_mfma_f32_16x16x32_bf16 v[54:57], v[152:155], v[176:179], v[54:57]
	v_mfma_f32_16x16x32_bf16 v[46:49], v[144:147], v[184:187], v[46:49]
	v_mfma_f32_16x16x32_bf16 v[38:41], v[152:155], v[184:187], v[38:41]
	v_mfma_f32_16x16x32_bf16 v[30:33], v[144:147], v[192:195], v[30:33]
	v_mfma_f32_16x16x32_bf16 v[22:25], v[152:155], v[192:195], v[22:25]
	v_mfma_f32_16x16x32_bf16 v[14:17], v[144:147], v[206:209], v[14:17]
	v_mfma_f32_16x16x32_bf16 v[6:9], v[152:155], v[206:209], v[6:9]
	v_mfma_f32_16x16x32_bf16 v[62:65], v[148:151], v[180:183], v[62:65]
	v_mfma_f32_16x16x32_bf16 v[54:57], v[156:159], v[180:183], v[54:57]
	v_mfma_f32_16x16x32_bf16 v[46:49], v[148:151], v[188:191], v[46:49]
	v_mfma_f32_16x16x32_bf16 v[38:41], v[156:159], v[188:191], v[38:41]
	v_mfma_f32_16x16x32_bf16 v[30:33], v[148:151], v[202:205], v[30:33]
	v_mfma_f32_16x16x32_bf16 v[22:25], v[156:159], v[202:205], v[22:25]
	v_mfma_f32_16x16x32_bf16 v[14:17], v[148:151], v[210:213], v[14:17]
	v_mfma_f32_16x16x32_bf16 v[6:9], v[156:159], v[210:213], v[6:9]
	s_setprio 0
	s_setprio 1
	v_mfma_f32_16x16x32_bf16 v[58:61], v[160:163], v[176:179], v[58:61]
	v_mfma_f32_16x16x32_bf16 v[50:53], v[168:171], v[176:179], v[50:53]
	v_mfma_f32_16x16x32_bf16 v[42:45], v[160:163], v[184:187], v[42:45]
	v_mfma_f32_16x16x32_bf16 v[34:37], v[168:171], v[184:187], v[34:37]
	v_mfma_f32_16x16x32_bf16 v[26:29], v[160:163], v[192:195], v[26:29]
	v_mfma_f32_16x16x32_bf16 v[18:21], v[168:171], v[192:195], v[18:21]
	v_mfma_f32_16x16x32_bf16 v[10:13], v[160:163], v[206:209], v[10:13]
	v_mfma_f32_16x16x32_bf16 v[2:5], v[168:171], v[206:209], v[2:5]
	v_mfma_f32_16x16x32_bf16 v[58:61], v[164:167], v[180:183], v[58:61]
	v_mfma_f32_16x16x32_bf16 v[50:53], v[172:175], v[180:183], v[50:53]
	v_mfma_f32_16x16x32_bf16 v[42:45], v[164:167], v[188:191], v[42:45]
	v_mfma_f32_16x16x32_bf16 v[34:37], v[172:175], v[188:191], v[34:37]
	v_mfma_f32_16x16x32_bf16 v[26:29], v[164:167], v[202:205], v[26:29]
	v_mfma_f32_16x16x32_bf16 v[18:21], v[172:175], v[202:205], v[18:21]
	v_mfma_f32_16x16x32_bf16 v[10:13], v[164:167], v[210:213], v[10:13]
	v_mfma_f32_16x16x32_bf16 v[2:5], v[172:175], v[210:213], v[2:5]
	s_setprio 0
	s_barrier
	s_add_i32 s70, 0, 0x18000
	s_add_i32 s71, 0, 0x1c000
	v_add_u32_e32 v156, s70, v141
	v_add_u32_e32 v172, s71, v141
	ds_read_b128 v[144:147], v156
	ds_read_b128 v[148:151], v156 offset:1024
	ds_read_b128 v[152:155], v156 offset:2048
	ds_read_b128 v[156:159], v156 offset:3072
	ds_read_b128 v[160:163], v172
	ds_read_b128 v[164:167], v172 offset:1024
	ds_read_b128 v[168:171], v172 offset:2048
	ds_read_b128 v[172:175], v172 offset:3072
	s_add_u32 s0, s58, 0x80000
	s_addc_u32 s1, s59, 0
	s_mov_b32 m0, s29
	v_lshl_add_u64 v[222:223], s[0:1], 0, v[134:135]
	ds_read_b128 v[176:179], v143 offset:32768
	ds_read_b128 v[180:183], v143 offset:33792
	ds_read_b128 v[184:187], v143 offset:34816
	ds_read_b128 v[188:191], v143 offset:35840
	ds_read_b128 v[192:195], v143 offset:36864
	ds_read_b128 v[202:205], v143 offset:37888
	ds_read_b128 v[206:209], v143 offset:38912
	ds_read_b128 v[210:213], v143 offset:39936
	global_load_lds_dwordx4 v[222:223], off
	v_lshl_add_u64 v[222:223], s[0:1], 0, v[132:133]
	s_mov_b32 m0, s30
	s_nop 0
	global_load_lds_dwordx4 v[222:223], off
	s_waitcnt vmcnt(8)
	s_waitcnt lgkmcnt(0)
	s_barrier
	s_setprio 1
	s_waitcnt lgkmcnt(0)
	v_mfma_f32_16x16x32_bf16 v[126:129], v[144:147], v[176:179], v[126:129]
	v_mfma_f32_16x16x32_bf16 v[118:121], v[152:155], v[176:179], v[118:121]
	v_mfma_f32_16x16x32_bf16 v[110:113], v[144:147], v[184:187], v[110:113]
	v_mfma_f32_16x16x32_bf16 v[102:105], v[152:155], v[184:187], v[102:105]
	v_mfma_f32_16x16x32_bf16 v[94:97], v[144:147], v[192:195], v[94:97]
	v_mfma_f32_16x16x32_bf16 v[86:89], v[152:155], v[192:195], v[86:89]
	v_mfma_f32_16x16x32_bf16 v[78:81], v[144:147], v[206:209], v[78:81]
	v_mfma_f32_16x16x32_bf16 v[70:73], v[152:155], v[206:209], v[70:73]
	v_mfma_f32_16x16x32_bf16 v[126:129], v[148:151], v[180:183], v[126:129]
	v_mfma_f32_16x16x32_bf16 v[118:121], v[156:159], v[180:183], v[118:121]
	v_mfma_f32_16x16x32_bf16 v[110:113], v[148:151], v[188:191], v[110:113]
	v_mfma_f32_16x16x32_bf16 v[102:105], v[156:159], v[188:191], v[102:105]
	v_mfma_f32_16x16x32_bf16 v[94:97], v[148:151], v[202:205], v[94:97]
	v_mfma_f32_16x16x32_bf16 v[86:89], v[156:159], v[202:205], v[86:89]
	v_mfma_f32_16x16x32_bf16 v[78:81], v[148:151], v[210:213], v[78:81]
	v_mfma_f32_16x16x32_bf16 v[70:73], v[156:159], v[210:213], v[70:73]
	s_setprio 0
	s_setprio 1
	v_mfma_f32_16x16x32_bf16 v[122:125], v[160:163], v[176:179], v[122:125]
	v_mfma_f32_16x16x32_bf16 v[114:117], v[168:171], v[176:179], v[114:117]
	v_mfma_f32_16x16x32_bf16 v[106:109], v[160:163], v[184:187], v[106:109]
	v_mfma_f32_16x16x32_bf16 v[98:101], v[168:171], v[184:187], v[98:101]
	v_mfma_f32_16x16x32_bf16 v[90:93], v[160:163], v[192:195], v[90:93]
	v_mfma_f32_16x16x32_bf16 v[82:85], v[168:171], v[192:195], v[82:85]
	v_mfma_f32_16x16x32_bf16 v[74:77], v[160:163], v[206:209], v[74:77]
	v_mfma_f32_16x16x32_bf16 v[66:69], v[168:171], v[206:209], v[66:69]
	v_mfma_f32_16x16x32_bf16 v[122:125], v[164:167], v[180:183], v[122:125]
	v_mfma_f32_16x16x32_bf16 v[114:117], v[172:175], v[180:183], v[114:117]
	v_mfma_f32_16x16x32_bf16 v[106:109], v[164:167], v[188:191], v[106:109]
	v_mfma_f32_16x16x32_bf16 v[98:101], v[172:175], v[188:191], v[98:101]
	v_mfma_f32_16x16x32_bf16 v[90:93], v[164:167], v[202:205], v[90:93]
	v_mfma_f32_16x16x32_bf16 v[82:85], v[172:175], v[202:205], v[82:85]
	v_mfma_f32_16x16x32_bf16 v[74:77], v[164:167], v[210:213], v[74:77]
	v_mfma_f32_16x16x32_bf16 v[66:69], v[172:175], v[210:213], v[66:69]
	s_setprio 0
	s_barrier
	s_add_i32 s0, s70, s26
	v_lshl_add_u64 v[214:215], v[214:215], 0, s[16:17]
	s_mov_b32 m0, s0
	ds_read_b128 v[176:179], v143 offset:49152
	ds_read_b128 v[180:183], v143 offset:50176
	ds_read_b128 v[184:187], v143 offset:51200
	ds_read_b128 v[188:191], v143 offset:52224
	ds_read_b128 v[192:195], v143 offset:53248
	ds_read_b128 v[202:205], v143 offset:54272
	ds_read_b128 v[206:209], v143 offset:55296
	ds_read_b128 v[210:213], v143 offset:56320
	global_load_lds_dwordx4 v[214:215], off
	s_add_i32 m0, s0, 0x2000
	s_add_u32 s0, s8, 0x80080
	v_lshl_add_u64 v[214:215], v[216:217], 0, s[16:17]
	s_addc_u32 s1, s9, 0
	s_add_i32 s8, s71, s26
	global_load_lds_dwordx4 v[214:215], off
	v_lshl_add_u64 v[214:215], s[0:1], 0, v[196:197]
	s_mov_b32 m0, s8
	s_nop 0
	global_load_lds_dwordx4 v[214:215], off
	v_lshl_add_u64 v[214:215], s[0:1], 0, v[130:131]
	s_add_i32 m0, s8, 0x2000
	s_nop 0
	global_load_lds_dwordx4 v[214:215], off
	v_lshl_add_u64 v[214:215], v[218:219], 0, s[16:17]
	s_mov_b32 m0, s31
	s_nop 0
	global_load_lds_dwordx4 v[214:215], off
	v_lshl_add_u64 v[214:215], v[220:221], 0, s[16:17]
	s_mov_b32 m0, s34
	s_nop 0
	global_load_lds_dwordx4 v[214:215], off
	s_waitcnt vmcnt(8)
	s_waitcnt lgkmcnt(0)
	s_barrier
	s_setprio 1
	s_waitcnt lgkmcnt(0)
	v_mfma_f32_16x16x32_bf16 v[62:65], v[144:147], v[176:179], v[62:65]
	v_mfma_f32_16x16x32_bf16 v[54:57], v[152:155], v[176:179], v[54:57]
	v_mfma_f32_16x16x32_bf16 v[46:49], v[144:147], v[184:187], v[46:49]
	v_mfma_f32_16x16x32_bf16 v[38:41], v[152:155], v[184:187], v[38:41]
	v_mfma_f32_16x16x32_bf16 v[30:33], v[144:147], v[192:195], v[30:33]
	v_mfma_f32_16x16x32_bf16 v[22:25], v[152:155], v[192:195], v[22:25]
	v_mfma_f32_16x16x32_bf16 v[14:17], v[144:147], v[206:209], v[14:17]
	v_mfma_f32_16x16x32_bf16 v[6:9], v[152:155], v[206:209], v[6:9]
	v_mfma_f32_16x16x32_bf16 v[62:65], v[148:151], v[180:183], v[62:65]
	v_mfma_f32_16x16x32_bf16 v[54:57], v[156:159], v[180:183], v[54:57]
	v_mfma_f32_16x16x32_bf16 v[46:49], v[148:151], v[188:191], v[46:49]
	v_mfma_f32_16x16x32_bf16 v[38:41], v[156:159], v[188:191], v[38:41]
	v_mfma_f32_16x16x32_bf16 v[30:33], v[148:151], v[202:205], v[30:33]
	v_mfma_f32_16x16x32_bf16 v[22:25], v[156:159], v[202:205], v[22:25]
	v_mfma_f32_16x16x32_bf16 v[14:17], v[148:151], v[210:213], v[14:17]
	v_mfma_f32_16x16x32_bf16 v[6:9], v[156:159], v[210:213], v[6:9]
	s_setprio 0
	s_setprio 1
	v_mfma_f32_16x16x32_bf16 v[58:61], v[160:163], v[176:179], v[58:61]
	v_mfma_f32_16x16x32_bf16 v[50:53], v[168:171], v[176:179], v[50:53]
	v_mfma_f32_16x16x32_bf16 v[42:45], v[160:163], v[184:187], v[42:45]
	v_mfma_f32_16x16x32_bf16 v[34:37], v[168:171], v[184:187], v[34:37]
	v_mfma_f32_16x16x32_bf16 v[26:29], v[160:163], v[192:195], v[26:29]
	v_mfma_f32_16x16x32_bf16 v[18:21], v[168:171], v[192:195], v[18:21]
	v_mfma_f32_16x16x32_bf16 v[10:13], v[160:163], v[206:209], v[10:13]
	v_mfma_f32_16x16x32_bf16 v[2:5], v[168:171], v[206:209], v[2:5]
	v_mfma_f32_16x16x32_bf16 v[58:61], v[164:167], v[180:183], v[58:61]
	v_mfma_f32_16x16x32_bf16 v[50:53], v[172:175], v[180:183], v[50:53]
	v_mfma_f32_16x16x32_bf16 v[42:45], v[164:167], v[188:191], v[42:45]
	v_mfma_f32_16x16x32_bf16 v[34:37], v[172:175], v[188:191], v[34:37]
	v_mfma_f32_16x16x32_bf16 v[26:29], v[164:167], v[202:205], v[26:29]
	v_mfma_f32_16x16x32_bf16 v[18:21], v[172:175], v[202:205], v[18:21]
	v_mfma_f32_16x16x32_bf16 v[10:13], v[164:167], v[210:213], v[10:13]
	v_mfma_f32_16x16x32_bf16 v[2:5], v[172:175], v[210:213], v[2:5]
	s_add_u32 s67, s67, 0x100
	s_addc_u32 s68, s68, 0
	s_add_u32 s52, s52, 0x100
	s_addc_u32 s53, s53, 0
	s_cmp_ge_i32 s69, s62
	s_mov_b32 s8, s69
	s_setprio 0
	s_barrier
	s_cbranch_scc0 .LBB0_2507
	s_and_b64 vcc, exec, s[38:39]
	s_cbranch_vccz .LBB0_2510
	s_barrier

.LBB0_2588:
	s_add_i32 s72, s48, 2
	s_add_u32 s8, s46, 0x100
	s_addc_u32 s9, s47, 0
	s_add_i32 s0, 0, 0x10000
	s_cmp_eq_u32 s41, s48
	s_cselect_b32 s51, s43, s9
	s_cselect_b32 s50, s42, s8
	s_cselect_b32 s49, s45, s71
	s_cselect_b32 s48, s44, s70
	s_add_i32 s73, 0, 0x14000
	v_add_u32_e32 v142, s0, v188
	v_add_u32_e32 v172, s73, v188
	ds_read_b128 v[130:133], v142
	ds_read_b128 v[134:137], v142 offset:1024
	ds_read_b128 v[138:141], v142 offset:2048
	ds_read_b128 v[142:145], v142 offset:3072
	ds_read_b128 v[146:149], v172
	ds_read_b128 v[164:167], v172 offset:1024
	ds_read_b128 v[168:171], v172 offset:2048
	ds_read_b128 v[172:175], v172 offset:3072
	v_lshl_add_u64 v[194:195], s[46:47], 0, v[162:163]
	s_add_i32 m0, s27, 0xc000
	ds_read_b128 v[176:179], v189
	ds_read_b128 v[180:183], v189 offset:1024
	ds_read_b128 v[184:187], v189 offset:2048
	ds_read_b128 v[190:193], v189 offset:3072
	ds_read_b128 v[202:205], v189 offset:4096
	ds_read_b128 v[206:209], v189 offset:5120
	ds_read_b128 v[210:213], v189 offset:6144
	ds_read_b128 v[214:217], v189 offset:7168
	global_load_lds_dwordx4 v[194:195], off
	v_lshl_add_u64 v[194:195], s[46:47], 0, v[160:161]
	s_add_i32 m0, s27, 0xe000
	s_nop 0
	global_load_lds_dwordx4 v[194:195], off
	s_waitcnt vmcnt(8)
	s_waitcnt lgkmcnt(0)
	s_barrier
	s_setprio 1
	s_waitcnt lgkmcnt(0)
	v_mfma_f32_16x16x32_bf16 v[126:129], v[130:133], v[176:179], v[126:129]
	v_mfma_f32_16x16x32_bf16 v[122:125], v[138:141], v[176:179], v[122:125]
	v_mfma_f32_16x16x32_bf16 v[110:113], v[130:133], v[184:187], v[110:113]
	v_mfma_f32_16x16x32_bf16 v[106:109], v[138:141], v[184:187], v[106:109]
	v_mfma_f32_16x16x32_bf16 v[98:101], v[130:133], v[202:205], v[98:101]
	v_mfma_f32_16x16x32_bf16 v[90:93], v[138:141], v[202:205], v[90:93]
	v_mfma_f32_16x16x32_bf16 v[82:85], v[130:133], v[210:213], v[82:85]
	v_mfma_f32_16x16x32_bf16 v[74:77], v[138:141], v[210:213], v[74:77]
	v_mfma_f32_16x16x32_bf16 v[126:129], v[134:137], v[180:183], v[126:129]
	v_mfma_f32_16x16x32_bf16 v[122:125], v[142:145], v[180:183], v[122:125]
	v_mfma_f32_16x16x32_bf16 v[110:113], v[134:137], v[190:193], v[110:113]
	v_mfma_f32_16x16x32_bf16 v[106:109], v[142:145], v[190:193], v[106:109]
	v_mfma_f32_16x16x32_bf16 v[98:101], v[134:137], v[206:209], v[98:101]
	v_mfma_f32_16x16x32_bf16 v[90:93], v[142:145], v[206:209], v[90:93]
	v_mfma_f32_16x16x32_bf16 v[82:85], v[134:137], v[214:217], v[82:85]
	v_mfma_f32_16x16x32_bf16 v[74:77], v[142:145], v[214:217], v[74:77]
	s_setprio 0
	s_setprio 1
	v_mfma_f32_16x16x32_bf16 v[118:121], v[146:149], v[176:179], v[118:121]
	v_mfma_f32_16x16x32_bf16 v[114:117], v[168:171], v[176:179], v[114:117]
	v_mfma_f32_16x16x32_bf16 v[102:105], v[146:149], v[184:187], v[102:105]
	v_mfma_f32_16x16x32_bf16 v[94:97], v[168:171], v[184:187], v[94:97]
	v_mfma_f32_16x16x32_bf16 v[86:89], v[146:149], v[202:205], v[86:89]
	v_mfma_f32_16x16x32_bf16 v[78:81], v[168:171], v[202:205], v[78:81]
	v_mfma_f32_16x16x32_bf16 v[70:73], v[146:149], v[210:213], v[70:73]
	v_mfma_f32_16x16x32_bf16 v[66:69], v[168:171], v[210:213], v[66:69]
	v_mfma_f32_16x16x32_bf16 v[118:121], v[164:167], v[180:183], v[118:121]
	v_mfma_f32_16x16x32_bf16 v[114:117], v[172:175], v[180:183], v[114:117]
	v_mfma_f32_16x16x32_bf16 v[102:105], v[164:167], v[190:193], v[102:105]
	v_mfma_f32_16x16x32_bf16 v[94:97], v[172:175], v[190:193], v[94:97]
	v_mfma_f32_16x16x32_bf16 v[86:89], v[164:167], v[206:209], v[86:89]
	v_mfma_f32_16x16x32_bf16 v[78:81], v[172:175], v[206:209], v[78:81]
	v_mfma_f32_16x16x32_bf16 v[70:73], v[164:167], v[214:217], v[70:73]
	v_mfma_f32_16x16x32_bf16 v[66:69], v[172:175], v[214:217], v[66:69]
	s_setprio 0
	s_barrier
	s_add_i32 s0, s0, s26
	v_lshl_add_u64 v[194:195], s[48:49], 0, v[196:197]
	s_mov_b32 m0, s0
	ds_read_b128 v[176:179], v189 offset:16384
	ds_read_b128 v[180:183], v189 offset:17408
	ds_read_b128 v[184:187], v189 offset:18432
	ds_read_b128 v[190:193], v189 offset:19456
	ds_read_b128 v[202:205], v189 offset:20480
	ds_read_b128 v[206:209], v189 offset:21504
	ds_read_b128 v[210:213], v189 offset:22528
	ds_read_b128 v[214:217], v189 offset:23552
	global_load_lds_dwordx4 v[194:195], off
	s_add_i32 m0, s0, 0x2000
	s_add_u32 s0, s48, 0x158000
	v_lshl_add_u64 v[218:219], s[48:49], 0, v[154:155]
	s_addc_u32 s1, s49, 0
	s_add_i32 s46, s73, s26
	global_load_lds_dwordx4 v[218:219], off
	v_lshl_add_u64 v[220:221], s[0:1], 0, v[196:197]
	s_mov_b32 m0, s46
	v_lshl_add_u64 v[222:223], s[50:51], 0, v[152:153]
	global_load_lds_dwordx4 v[220:221], off
	v_lshl_add_u64 v[220:221], s[0:1], 0, v[154:155]
	s_add_i32 m0, s46, 0x2000
	s_nop 0
	global_load_lds_dwordx4 v[220:221], off
	v_lshl_add_u64 v[220:221], s[50:51], 0, v[150:151]
	s_mov_b32 m0, s27
	s_nop 0
	global_load_lds_dwordx4 v[220:221], off
	s_mov_b32 m0, s30
	s_nop 0
	global_load_lds_dwordx4 v[222:223], off
	s_waitcnt vmcnt(8)
	s_waitcnt lgkmcnt(0)
	s_barrier
	s_setprio 1
	s_waitcnt lgkmcnt(0)
	v_mfma_f32_16x16x32_bf16 v[62:65], v[130:133], v[176:179], v[62:65]
	v_mfma_f32_16x16x32_bf16 v[58:61], v[138:141], v[176:179], v[58:61]
	v_mfma_f32_16x16x32_bf16 v[50:53], v[130:133], v[184:187], v[50:53]
	v_mfma_f32_16x16x32_bf16 v[42:45], v[138:141], v[184:187], v[42:45]
	v_mfma_f32_16x16x32_bf16 v[34:37], v[130:133], v[202:205], v[34:37]
	v_mfma_f32_16x16x32_bf16 v[26:29], v[138:141], v[202:205], v[26:29]
	v_mfma_f32_16x16x32_bf16 v[18:21], v[130:133], v[210:213], v[18:21]
	v_mfma_f32_16x16x32_bf16 v[10:13], v[138:141], v[210:213], v[10:13]
	v_mfma_f32_16x16x32_bf16 v[62:65], v[134:137], v[180:183], v[62:65]
	v_mfma_f32_16x16x32_bf16 v[58:61], v[142:145], v[180:183], v[58:61]
	v_mfma_f32_16x16x32_bf16 v[50:53], v[134:137], v[190:193], v[50:53]
	v_mfma_f32_16x16x32_bf16 v[42:45], v[142:145], v[190:193], v[42:45]
	v_mfma_f32_16x16x32_bf16 v[34:37], v[134:137], v[206:209], v[34:37]
	v_mfma_f32_16x16x32_bf16 v[26:29], v[142:145], v[206:209], v[26:29]
	v_mfma_f32_16x16x32_bf16 v[18:21], v[134:137], v[214:217], v[18:21]
	v_mfma_f32_16x16x32_bf16 v[10:13], v[142:145], v[214:217], v[10:13]
	s_setprio 0
	s_setprio 1
	v_mfma_f32_16x16x32_bf16 v[54:57], v[146:149], v[176:179], v[54:57]
	v_mfma_f32_16x16x32_bf16 v[46:49], v[168:171], v[176:179], v[46:49]
	v_mfma_f32_16x16x32_bf16 v[38:41], v[146:149], v[184:187], v[38:41]
	v_mfma_f32_16x16x32_bf16 v[30:33], v[168:171], v[184:187], v[30:33]
	v_mfma_f32_16x16x32_bf16 v[22:25], v[146:149], v[202:205], v[22:25]
	v_mfma_f32_16x16x32_bf16 v[14:17], v[168:171], v[202:205], v[14:17]
	v_mfma_f32_16x16x32_bf16 v[6:9], v[146:149], v[210:213], v[6:9]
	v_mfma_f32_16x16x32_bf16 v[2:5], v[168:171], v[210:213], v[2:5]
	v_mfma_f32_16x16x32_bf16 v[54:57], v[164:167], v[180:183], v[54:57]
	v_mfma_f32_16x16x32_bf16 v[46:49], v[172:175], v[180:183], v[46:49]
	v_mfma_f32_16x16x32_bf16 v[38:41], v[164:167], v[190:193], v[38:41]
	v_mfma_f32_16x16x32_bf16 v[30:33], v[172:175], v[190:193], v[30:33]
	v_mfma_f32_16x16x32_bf16 v[22:25], v[164:167], v[206:209], v[22:25]
	v_mfma_f32_16x16x32_bf16 v[14:17], v[172:175], v[206:209], v[14:17]
	v_mfma_f32_16x16x32_bf16 v[6:9], v[164:167], v[214:217], v[6:9]
	v_mfma_f32_16x16x32_bf16 v[2:5], v[172:175], v[214:217], v[2:5]
	s_setprio 0
	s_barrier
	s_add_i32 s46, 0, 0x18000
	s_add_i32 s47, 0, 0x1c000
	v_add_u32_e32 v142, s46, v188
	v_add_u32_e32 v172, s47, v188
	ds_read_b128 v[130:133], v142
	ds_read_b128 v[134:137], v142 offset:1024
	ds_read_b128 v[138:141], v142 offset:2048
	ds_read_b128 v[142:145], v142 offset:3072
	ds_read_b128 v[146:149], v172
	ds_read_b128 v[164:167], v172 offset:1024
	ds_read_b128 v[168:171], v172 offset:2048
	ds_read_b128 v[172:175], v172 offset:3072
	s_add_u32 s0, s50, 0x158000
	s_addc_u32 s1, s51, 0
	s_mov_b32 m0, s31
	v_lshl_add_u64 v[224:225], s[0:1], 0, v[150:151]
	ds_read_b128 v[176:179], v189 offset:32768
	ds_read_b128 v[180:183], v189 offset:33792
	ds_read_b128 v[184:187], v189 offset:34816
	ds_read_b128 v[190:193], v189 offset:35840
	ds_read_b128 v[202:205], v189 offset:36864
	ds_read_b128 v[206:209], v189 offset:37888
	ds_read_b128 v[210:213], v189 offset:38912
	ds_read_b128 v[214:217], v189 offset:39936
	global_load_lds_dwordx4 v[224:225], off
	v_lshl_add_u64 v[224:225], s[0:1], 0, v[152:153]
	s_mov_b32 m0, s34
	s_nop 0
	global_load_lds_dwordx4 v[224:225], off
	s_waitcnt vmcnt(8)
	s_waitcnt lgkmcnt(0)
	s_barrier
	s_setprio 1
	s_waitcnt lgkmcnt(0)
	v_mfma_f32_16x16x32_bf16 v[126:129], v[130:133], v[176:179], v[126:129]
	v_mfma_f32_16x16x32_bf16 v[122:125], v[138:141], v[176:179], v[122:125]
	v_mfma_f32_16x16x32_bf16 v[110:113], v[130:133], v[184:187], v[110:113]
	v_mfma_f32_16x16x32_bf16 v[106:109], v[138:141], v[184:187], v[106:109]
	v_mfma_f32_16x16x32_bf16 v[98:101], v[130:133], v[202:205], v[98:101]
	v_mfma_f32_16x16x32_bf16 v[90:93], v[138:141], v[202:205], v[90:93]
	v_mfma_f32_16x16x32_bf16 v[82:85], v[130:133], v[210:213], v[82:85]
	v_mfma_f32_16x16x32_bf16 v[74:77], v[138:141], v[210:213], v[74:77]
	v_mfma_f32_16x16x32_bf16 v[126:129], v[134:137], v[180:183], v[126:129]
	v_mfma_f32_16x16x32_bf16 v[122:125], v[142:145], v[180:183], v[122:125]
	v_mfma_f32_16x16x32_bf16 v[110:113], v[134:137], v[190:193], v[110:113]
	v_mfma_f32_16x16x32_bf16 v[106:109], v[142:145], v[190:193], v[106:109]
	v_mfma_f32_16x16x32_bf16 v[98:101], v[134:137], v[206:209], v[98:101]
	v_mfma_f32_16x16x32_bf16 v[90:93], v[142:145], v[206:209], v[90:93]
	v_mfma_f32_16x16x32_bf16 v[82:85], v[134:137], v[214:217], v[82:85]
	v_mfma_f32_16x16x32_bf16 v[74:77], v[142:145], v[214:217], v[74:77]
	s_setprio 0
	s_setprio 1
	v_mfma_f32_16x16x32_bf16 v[118:121], v[146:149], v[176:179], v[118:121]
	v_mfma_f32_16x16x32_bf16 v[114:117], v[168:171], v[176:179], v[114:117]
	v_mfma_f32_16x16x32_bf16 v[102:105], v[146:149], v[184:187], v[102:105]
	v_mfma_f32_16x16x32_bf16 v[94:97], v[168:171], v[184:187], v[94:97]
	v_mfma_f32_16x16x32_bf16 v[86:89], v[146:149], v[202:205], v[86:89]
	v_mfma_f32_16x16x32_bf16 v[78:81], v[168:171], v[202:205], v[78:81]
	v_mfma_f32_16x16x32_bf16 v[70:73], v[146:149], v[210:213], v[70:73]
	v_mfma_f32_16x16x32_bf16 v[66:69], v[168:171], v[210:213], v[66:69]
	v_mfma_f32_16x16x32_bf16 v[118:121], v[164:167], v[180:183], v[118:121]
	v_mfma_f32_16x16x32_bf16 v[114:117], v[172:175], v[180:183], v[114:117]
	v_mfma_f32_16x16x32_bf16 v[102:105], v[164:167], v[190:193], v[102:105]
	v_mfma_f32_16x16x32_bf16 v[94:97], v[172:175], v[190:193], v[94:97]
	v_mfma_f32_16x16x32_bf16 v[86:89], v[164:167], v[206:209], v[86:89]
	v_mfma_f32_16x16x32_bf16 v[78:81], v[172:175], v[206:209], v[78:81]
	v_mfma_f32_16x16x32_bf16 v[70:73], v[164:167], v[214:217], v[70:73]
	v_mfma_f32_16x16x32_bf16 v[66:69], v[172:175], v[214:217], v[66:69]
	s_setprio 0
	s_barrier
	s_add_i32 s0, s46, s26
	v_lshl_add_u64 v[194:195], v[194:195], 0, s[16:17]
	s_mov_b32 m0, s0
	ds_read_b128 v[176:179], v189 offset:49152
	ds_read_b128 v[180:183], v189 offset:50176
	ds_read_b128 v[184:187], v189 offset:51200
	ds_read_b128 v[190:193], v189 offset:52224
	ds_read_b128 v[202:205], v189 offset:53248
	ds_read_b128 v[206:209], v189 offset:54272
	ds_read_b128 v[210:213], v189 offset:55296
	ds_read_b128 v[214:217], v189 offset:56320
	global_load_lds_dwordx4 v[194:195], off
	s_add_i32 m0, s0, 0x2000
	s_add_u32 s0, s48, 0x158080
	v_lshl_add_u64 v[194:195], v[218:219], 0, s[16:17]
	s_addc_u32 s1, s49, 0
	s_add_i32 s46, s47, s26
	global_load_lds_dwordx4 v[194:195], off
	v_lshl_add_u64 v[194:195], s[0:1], 0, v[196:197]
	s_mov_b32 m0, s46
	s_nop 0
	global_load_lds_dwordx4 v[194:195], off
	v_lshl_add_u64 v[194:195], s[0:1], 0, v[154:155]
	s_add_i32 m0, s46, 0x2000
	s_nop 0
	global_load_lds_dwordx4 v[194:195], off
	v_lshl_add_u64 v[194:195], v[220:221], 0, s[16:17]
	s_mov_b32 m0, s53
	s_nop 0
	global_load_lds_dwordx4 v[194:195], off
	v_lshl_add_u64 v[194:195], v[222:223], 0, s[16:17]
	s_mov_b32 m0, s58
	s_nop 0
	global_load_lds_dwordx4 v[194:195], off
	s_waitcnt vmcnt(8)
	s_waitcnt lgkmcnt(0)
	s_barrier
	s_setprio 1
	s_waitcnt lgkmcnt(0)
	v_mfma_f32_16x16x32_bf16 v[62:65], v[130:133], v[176:179], v[62:65]
	v_mfma_f32_16x16x32_bf16 v[58:61], v[138:141], v[176:179], v[58:61]
	v_mfma_f32_16x16x32_bf16 v[50:53], v[130:133], v[184:187], v[50:53]
	v_mfma_f32_16x16x32_bf16 v[42:45], v[138:141], v[184:187], v[42:45]
	v_mfma_f32_16x16x32_bf16 v[34:37], v[130:133], v[202:205], v[34:37]
	v_mfma_f32_16x16x32_bf16 v[26:29], v[138:141], v[202:205], v[26:29]
	v_mfma_f32_16x16x32_bf16 v[18:21], v[130:133], v[210:213], v[18:21]
	v_mfma_f32_16x16x32_bf16 v[10:13], v[138:141], v[210:213], v[10:13]
	v_mfma_f32_16x16x32_bf16 v[62:65], v[134:137], v[180:183], v[62:65]
	v_mfma_f32_16x16x32_bf16 v[58:61], v[142:145], v[180:183], v[58:61]
	v_mfma_f32_16x16x32_bf16 v[50:53], v[134:137], v[190:193], v[50:53]
	v_mfma_f32_16x16x32_bf16 v[42:45], v[142:145], v[190:193], v[42:45]
	v_mfma_f32_16x16x32_bf16 v[34:37], v[134:137], v[206:209], v[34:37]
	v_mfma_f32_16x16x32_bf16 v[26:29], v[142:145], v[206:209], v[26:29]
	v_mfma_f32_16x16x32_bf16 v[18:21], v[134:137], v[214:217], v[18:21]
	v_mfma_f32_16x16x32_bf16 v[10:13], v[142:145], v[214:217], v[10:13]
	s_setprio 0
	s_setprio 1
	v_mfma_f32_16x16x32_bf16 v[54:57], v[146:149], v[176:179], v[54:57]
	v_mfma_f32_16x16x32_bf16 v[46:49], v[168:171], v[176:179], v[46:49]
	v_mfma_f32_16x16x32_bf16 v[38:41], v[146:149], v[184:187], v[38:41]
	v_mfma_f32_16x16x32_bf16 v[30:33], v[168:171], v[184:187], v[30:33]
	v_mfma_f32_16x16x32_bf16 v[22:25], v[146:149], v[202:205], v[22:25]
	v_mfma_f32_16x16x32_bf16 v[14:17], v[168:171], v[202:205], v[14:17]
	v_mfma_f32_16x16x32_bf16 v[6:9], v[146:149], v[210:213], v[6:9]
	v_mfma_f32_16x16x32_bf16 v[2:5], v[168:171], v[210:213], v[2:5]
	v_mfma_f32_16x16x32_bf16 v[54:57], v[164:167], v[180:183], v[54:57]
	v_mfma_f32_16x16x32_bf16 v[46:49], v[172:175], v[180:183], v[46:49]
	v_mfma_f32_16x16x32_bf16 v[38:41], v[164:167], v[190:193], v[38:41]
	v_mfma_f32_16x16x32_bf16 v[30:33], v[172:175], v[190:193], v[30:33]
	v_mfma_f32_16x16x32_bf16 v[22:25], v[164:167], v[206:209], v[22:25]
	v_mfma_f32_16x16x32_bf16 v[14:17], v[172:175], v[206:209], v[14:17]
	v_mfma_f32_16x16x32_bf16 v[6:9], v[164:167], v[214:217], v[6:9]
	v_mfma_f32_16x16x32_bf16 v[2:5], v[172:175], v[214:217], v[2:5]
	s_add_u32 s70, s70, 0x100
	s_addc_u32 s71, s71, 0
	s_cmp_ge_i32 s72, s69
	s_mov_b64 s[46:47], s[8:9]
	s_mov_b32 s48, s72
	s_setprio 0
	s_barrier
	s_cbranch_scc0 .LBB0_2588
	s_and_b64 vcc, exec, s[28:29]
	s_cbranch_vccz .LBB0_2591
	s_barrier
